# persistent 128x128 GEMM bodies (seamless cross-tile k-pipeline, next-tile loads in last two steps) for w1,inproj,wout,w2
# speedup vs baseline: 1.0395x; 1.0083x over previous
.LBB0_24:
	s_andn2_b64 vcc, exec, s[4:5]
	s_cbranch_vccnz .LBB0_30
	v_readlane_b32 s4, v239, 0
	v_readlane_b32 s5, v239, 1
	s_andn2_b64 vcc, exec, s[4:5]
	s_cbranch_vccnz .LBB0_30
	s_load_dwordx2 s[4:5], s[0:1], 0x130
	s_load_dwordx2 s[24:25], s[0:1], 0x128
	v_and_b32_e32 v0, 63, v133
	v_lshrrev_b32_e32 v131, 6, v133
	v_lshrrev_b32_e32 v195, 2, v0
	v_readfirstlane_b32 s15, v131
	v_mul_u32_u24_e32 v177, 0x2000, v195
	v_and_b32_e32 v195, 3, v0
	v_lshlrev_b32_e32 v195, 4, v195
	v_lshrrev_b32_e32 v131, 5, v0
	v_lshlrev_b32_e32 v131, 5, v131
	v_xor_b32_e32 v195, v195, v131
	v_add_u32_e32 v177, v177, v195
	v_and_b32_e32 v195, 15, v0
	v_lshrrev_b32_e32 v131, 4, v0
	v_lshlrev_b32_e32 v141, 6, v195
	v_lshl_or_b32 v141, v131, 4, v141
	v_and_b32_e32 v178, 8, v0
	v_lshlrev_b32_e32 v178, 2, v178
	v_xor_b32_e32 v141, v141, v178
	v_mul_u32_u24_e32 v178, 0x1000, v195
	v_lshl_or_b32 v178, v131, 4, v178
	s_waitcnt lgkmcnt(0)
	s_add_u32 s18, s4, 0x4b27800
	s_addc_u32 s19, s5, 0
	s_add_u32 s20, s4, 0x2327800
	s_addc_u32 s21, s5, 0
	s_mul_i32 s3, s62, 73728
	s_add_u32 s3, s3, 20480
	s_add_u32 s4, s4, s3
	s_addc_u32 s5, s5, 0
	v_lshlrev_b32_e32 v143, 4, v131
	s_and_b32 s3, s15, 1
	s_lshl_b32 s3, s3, 13
	s_add_u32 s3, s3, 16384
	v_add_u32_e32 v142, s3, v141
	s_lshr_b32 s3, s15, 1
	s_lshl_b32 s3, s3, 13
	v_add_u32_e32 v141, s3, v141
	s_lshl_b32 s22, s15, 12
	s_mov_b32 s12, s79
.Lg128_w2_first_retry:
	s_cmp_ge_u32 s12, 128
	s_cbranch_scc1 .Lg128_w2_done
	s_lshr_b32 s3, s12, 6
	s_lshl_b32 s3, s3, 3
	s_add_u32 s3, s3, s65
	s_mov_b32 s17, s3
	s_mov_b32 s3, 0
	s_lshl_b32 s17, s17, 3
	s_bfe_u32 s23, s12, 0x30003
	s_add_u32 s13, s17, s23
	s_lshl_b32 s3, s3, 3
	s_and_b32 s23, s12, 7
	s_add_u32 s14, s3, s23
	s_lshl_b32 s13, s13, 7
	s_lshl_b32 s14, s14, 7
	s_lshl_b32 s3, s15, 5
	s_add_u32 s17, s3, s13
	s_mul_i32 s17, s17, 0x2000
	s_add_u32 s6, s18, s17
	s_addc_u32 s7, s19, 0
	s_add_u32 s17, s3, s14
	s_mul_i32 s17, s17, 0x2000
	s_add_u32 s8, s20, s17
	s_addc_u32 s9, s21, 0
	s_barrier
	v_mov_b32_e32 v176, v177
	s_add_u32 m0, s22, 0x0
	v_mov_b32_e32 v179, v176
	global_load_lds_dwordx4 v179, s[6:7]
	s_add_u32 m0, s22, 0x400
	v_add_u32_e32 v180, 0x40, v176
	global_load_lds_dwordx4 v180, s[6:7]
	s_add_u32 m0, s22, 0x800
	v_add_u32_e32 v179, 0x20000, v176
	global_load_lds_dwordx4 v179, s[6:7]
	s_add_u32 m0, s22, 0xc00
	v_add_u32_e32 v180, 0x20040, v176
	global_load_lds_dwordx4 v180, s[6:7]
	s_add_u32 m0, s22, 0x4000
	v_mov_b32_e32 v179, v176
	global_load_lds_dwordx4 v179, s[8:9]
	s_add_u32 m0, s22, 0x4400
	v_add_u32_e32 v180, 0x40, v176
	global_load_lds_dwordx4 v180, s[8:9]
	s_add_u32 m0, s22, 0x4800
	v_add_u32_e32 v179, 0x20000, v176
	global_load_lds_dwordx4 v179, s[8:9]
	s_add_u32 m0, s22, 0x4c00
	v_add_u32_e32 v180, 0x20040, v176
	global_load_lds_dwordx4 v180, s[8:9]
	v_add_u32_e32 v176, 0x80, v176
	s_add_u32 m0, s22, 0x8000
	v_mov_b32_e32 v179, v176
	global_load_lds_dwordx4 v179, s[6:7]
	s_add_u32 m0, s22, 0x8400
	v_add_u32_e32 v180, 0x40, v176
	global_load_lds_dwordx4 v180, s[6:7]
	s_add_u32 m0, s22, 0x8800
	v_add_u32_e32 v179, 0x20000, v176
	global_load_lds_dwordx4 v179, s[6:7]
	s_add_u32 m0, s22, 0x8c00
	v_add_u32_e32 v180, 0x20040, v176
	global_load_lds_dwordx4 v180, s[6:7]
	s_add_u32 m0, s22, 0xc000
	v_mov_b32_e32 v179, v176
	global_load_lds_dwordx4 v179, s[8:9]
	s_add_u32 m0, s22, 0xc400
	v_add_u32_e32 v180, 0x40, v176
	global_load_lds_dwordx4 v180, s[8:9]
	s_add_u32 m0, s22, 0xc800
	v_add_u32_e32 v179, 0x20000, v176
	global_load_lds_dwordx4 v179, s[8:9]
	s_add_u32 m0, s22, 0xcc00
	v_add_u32_e32 v180, 0x20040, v176
	global_load_lds_dwordx4 v180, s[8:9]
	v_add_u32_e32 v176, 0x80, v176
	s_waitcnt vmcnt(0)
	s_barrier
	ds_read_b128 v[90:93], v142
	ds_read_b128 v[94:97], v142 offset:2048
	ds_read_b128 v[98:101], v142 offset:4096
	ds_read_b128 v[102:105], v142 offset:6144
	ds_read_b128 v[106:109], v141
	ds_read_b128 v[110:113], v141 offset:2048
	ds_read_b128 v[114:117], v141 offset:4096
	ds_read_b128 v[118:121], v141 offset:6144
.Lg128_w2_tile:
	s_lshr_b32 s3, s15, 1
	s_lshl_b32 s3, s3, 6
	s_add_u32 s3, s3, s13
	s_mul_i32 s17, s3, 0x1000
	s_and_b32 s3, s15, 1
	s_lshl_b32 s3, s3, 6
	s_add_u32 s3, s3, s14
	s_mul_i32 s3, s3, 4
	s_add_u32 s17, s17, s3
	s_add_u32 s10, s24, s17
	s_addc_u32 s11, s25, 0
	s_lshr_b32 s17, s13, 12
	s_max_u32 s17, s17, 1
	s_sub_u32 s17, s17, 1
	s_mul_i32 s17, s17, 24576
	s_add_u32 s3, s3, s17
	v_add_u32_e32 v181, s3, v143
	s_mov_b64 s[26:27], s[10:11]
	s_waitcnt lgkmcnt(0)
	v_mfma_f32_16x16x32_bf16 v[2:5], v[90:93], v[106:109], 0
	ds_read_b128 v[144:147], v142 offset:1024
	v_mfma_f32_16x16x32_bf16 v[6:9], v[94:97], v[106:109], 0
	ds_read_b128 v[148:151], v142 offset:3072
	v_mfma_f32_16x16x32_bf16 v[10:13], v[98:101], v[106:109], 0
	ds_read_b128 v[152:155], v142 offset:5120
	v_mfma_f32_16x16x32_bf16 v[14:17], v[102:105], v[106:109], 0
	ds_read_b128 v[156:159], v142 offset:7168
	v_mfma_f32_16x16x32_bf16 v[18:21], v[90:93], v[110:113], 0
	ds_read_b128 v[160:163], v141 offset:1024
	v_mfma_f32_16x16x32_bf16 v[22:25], v[94:97], v[110:113], 0
	ds_read_b128 v[164:167], v141 offset:3072
	v_mfma_f32_16x16x32_bf16 v[26:29], v[98:101], v[110:113], 0
	ds_read_b128 v[168:171], v141 offset:5120
	v_mfma_f32_16x16x32_bf16 v[30:33], v[102:105], v[110:113], 0
	ds_read_b128 v[172:175], v141 offset:7168
	v_mfma_f32_16x16x32_bf16 v[34:37], v[90:93], v[114:117], 0
	v_mfma_f32_16x16x32_bf16 v[38:41], v[94:97], v[114:117], 0
	v_mfma_f32_16x16x32_bf16 v[42:45], v[98:101], v[114:117], 0
	v_mfma_f32_16x16x32_bf16 v[46:49], v[102:105], v[114:117], 0
	v_mfma_f32_16x16x32_bf16 v[50:53], v[90:93], v[118:121], 0
	v_mfma_f32_16x16x32_bf16 v[54:57], v[94:97], v[118:121], 0
	v_mfma_f32_16x16x32_bf16 v[58:61], v[98:101], v[118:121], 0
	v_mfma_f32_16x16x32_bf16 v[62:65], v[102:105], v[118:121], 0
	s_waitcnt vmcnt(16) lgkmcnt(0)
	s_barrier
	v_mfma_f32_16x16x32_bf16 v[2:5], v[144:147], v[160:163], v[2:5]
	ds_read_b128 v[90:93], v142 offset:32768
	s_add_u32 m0, s22, 0x0
	v_mov_b32_e32 v179, v176
	global_load_lds_dwordx4 v179, s[6:7]
	v_mfma_f32_16x16x32_bf16 v[6:9], v[148:151], v[160:163], v[6:9]
	ds_read_b128 v[94:97], v142 offset:34816
	s_add_u32 m0, s22, 0x400
	v_add_u32_e32 v180, 0x40, v176
	global_load_lds_dwordx4 v180, s[6:7]
	v_mfma_f32_16x16x32_bf16 v[10:13], v[152:155], v[160:163], v[10:13]
	ds_read_b128 v[98:101], v142 offset:36864
	s_add_u32 m0, s22, 0x800
	v_add_u32_e32 v179, 0x20000, v176
	global_load_lds_dwordx4 v179, s[6:7]
	v_mfma_f32_16x16x32_bf16 v[14:17], v[156:159], v[160:163], v[14:17]
	ds_read_b128 v[102:105], v142 offset:38912
	s_add_u32 m0, s22, 0xc00
	v_add_u32_e32 v180, 0x20040, v176
	global_load_lds_dwordx4 v180, s[6:7]
	v_mfma_f32_16x16x32_bf16 v[18:21], v[144:147], v[164:167], v[18:21]
	ds_read_b128 v[106:109], v141 offset:32768
	s_add_u32 m0, s22, 0x4000
	v_mov_b32_e32 v179, v176
	global_load_lds_dwordx4 v179, s[8:9]
	v_mfma_f32_16x16x32_bf16 v[22:25], v[148:151], v[164:167], v[22:25]
	ds_read_b128 v[110:113], v141 offset:34816
	s_add_u32 m0, s22, 0x4400
	v_add_u32_e32 v180, 0x40, v176
	global_load_lds_dwordx4 v180, s[8:9]
	v_mfma_f32_16x16x32_bf16 v[26:29], v[152:155], v[164:167], v[26:29]
	ds_read_b128 v[114:117], v141 offset:36864
	s_add_u32 m0, s22, 0x4800
	v_add_u32_e32 v179, 0x20000, v176
	global_load_lds_dwordx4 v179, s[8:9]
	v_mfma_f32_16x16x32_bf16 v[30:33], v[156:159], v[164:167], v[30:33]
	ds_read_b128 v[118:121], v141 offset:38912
	s_add_u32 m0, s22, 0x4c00
	v_add_u32_e32 v180, 0x20040, v176
	global_load_lds_dwordx4 v180, s[8:9]
	v_mfma_f32_16x16x32_bf16 v[34:37], v[144:147], v[168:171], v[34:37]
	v_mfma_f32_16x16x32_bf16 v[38:41], v[148:151], v[168:171], v[38:41]
	v_mfma_f32_16x16x32_bf16 v[42:45], v[152:155], v[168:171], v[42:45]
	v_mfma_f32_16x16x32_bf16 v[46:49], v[156:159], v[168:171], v[46:49]
	v_mfma_f32_16x16x32_bf16 v[50:53], v[144:147], v[172:175], v[50:53]
	v_mfma_f32_16x16x32_bf16 v[54:57], v[148:151], v[172:175], v[54:57]
	v_mfma_f32_16x16x32_bf16 v[58:61], v[152:155], v[172:175], v[58:61]
	v_mfma_f32_16x16x32_bf16 v[62:65], v[156:159], v[172:175], v[62:65]
	v_add_u32_e32 v176, 0x80, v176
	s_waitcnt lgkmcnt(0)
	v_mfma_f32_16x16x32_bf16 v[2:5], v[90:93], v[106:109], v[2:5]
	ds_read_b128 v[144:147], v142 offset:33792
	v_mfma_f32_16x16x32_bf16 v[6:9], v[94:97], v[106:109], v[6:9]
	ds_read_b128 v[148:151], v142 offset:35840
	v_mfma_f32_16x16x32_bf16 v[10:13], v[98:101], v[106:109], v[10:13]
	ds_read_b128 v[152:155], v142 offset:37888
	v_mfma_f32_16x16x32_bf16 v[14:17], v[102:105], v[106:109], v[14:17]
	ds_read_b128 v[156:159], v142 offset:39936
	v_mfma_f32_16x16x32_bf16 v[18:21], v[90:93], v[110:113], v[18:21]
	ds_read_b128 v[160:163], v141 offset:33792
	v_mfma_f32_16x16x32_bf16 v[22:25], v[94:97], v[110:113], v[22:25]
	ds_read_b128 v[164:167], v141 offset:35840
	v_mfma_f32_16x16x32_bf16 v[26:29], v[98:101], v[110:113], v[26:29]
	ds_read_b128 v[168:171], v141 offset:37888
	v_mfma_f32_16x16x32_bf16 v[30:33], v[102:105], v[110:113], v[30:33]
	ds_read_b128 v[172:175], v141 offset:39936
	v_mfma_f32_16x16x32_bf16 v[34:37], v[90:93], v[114:117], v[34:37]
	v_mfma_f32_16x16x32_bf16 v[38:41], v[94:97], v[114:117], v[38:41]
	v_mfma_f32_16x16x32_bf16 v[42:45], v[98:101], v[114:117], v[42:45]
	v_mfma_f32_16x16x32_bf16 v[46:49], v[102:105], v[114:117], v[46:49]
	v_mfma_f32_16x16x32_bf16 v[50:53], v[90:93], v[118:121], v[50:53]
	v_mfma_f32_16x16x32_bf16 v[54:57], v[94:97], v[118:121], v[54:57]
	v_mfma_f32_16x16x32_bf16 v[58:61], v[98:101], v[118:121], v[58:61]
	v_mfma_f32_16x16x32_bf16 v[62:65], v[102:105], v[118:121], v[62:65]
	s_waitcnt vmcnt(0) lgkmcnt(0)
	s_barrier
	v_mfma_f32_16x16x32_bf16 v[2:5], v[144:147], v[160:163], v[2:5]
	ds_read_b128 v[90:93], v142
	s_add_u32 m0, s22, 0x8000
	v_mov_b32_e32 v179, v176
	global_load_lds_dwordx4 v179, s[6:7]
	v_mfma_f32_16x16x32_bf16 v[6:9], v[148:151], v[160:163], v[6:9]
	ds_read_b128 v[94:97], v142 offset:2048
	s_add_u32 m0, s22, 0x8400
	v_add_u32_e32 v180, 0x40, v176
	global_load_lds_dwordx4 v180, s[6:7]
	v_mfma_f32_16x16x32_bf16 v[10:13], v[152:155], v[160:163], v[10:13]
	ds_read_b128 v[98:101], v142 offset:4096
	s_add_u32 m0, s22, 0x8800
	v_add_u32_e32 v179, 0x20000, v176
	global_load_lds_dwordx4 v179, s[6:7]
	v_mfma_f32_16x16x32_bf16 v[14:17], v[156:159], v[160:163], v[14:17]
	ds_read_b128 v[102:105], v142 offset:6144
	s_add_u32 m0, s22, 0x8c00
	v_add_u32_e32 v180, 0x20040, v176
	global_load_lds_dwordx4 v180, s[6:7]
	v_mfma_f32_16x16x32_bf16 v[18:21], v[144:147], v[164:167], v[18:21]
	ds_read_b128 v[106:109], v141
	s_add_u32 m0, s22, 0xc000
	v_mov_b32_e32 v179, v176
	global_load_lds_dwordx4 v179, s[8:9]
	v_mfma_f32_16x16x32_bf16 v[22:25], v[148:151], v[164:167], v[22:25]
	ds_read_b128 v[110:113], v141 offset:2048
	s_add_u32 m0, s22, 0xc400
	v_add_u32_e32 v180, 0x40, v176
	global_load_lds_dwordx4 v180, s[8:9]
	v_mfma_f32_16x16x32_bf16 v[26:29], v[152:155], v[164:167], v[26:29]
	ds_read_b128 v[114:117], v141 offset:4096
	s_add_u32 m0, s22, 0xc800
	v_add_u32_e32 v179, 0x20000, v176
	global_load_lds_dwordx4 v179, s[8:9]
	v_mfma_f32_16x16x32_bf16 v[30:33], v[156:159], v[164:167], v[30:33]
	ds_read_b128 v[118:121], v141 offset:6144
	s_add_u32 m0, s22, 0xcc00
	v_add_u32_e32 v180, 0x20040, v176
	global_load_lds_dwordx4 v180, s[8:9]
	v_mfma_f32_16x16x32_bf16 v[34:37], v[144:147], v[168:171], v[34:37]
	v_mfma_f32_16x16x32_bf16 v[38:41], v[148:151], v[168:171], v[38:41]
	v_mfma_f32_16x16x32_bf16 v[42:45], v[152:155], v[168:171], v[42:45]
	v_mfma_f32_16x16x32_bf16 v[46:49], v[156:159], v[168:171], v[46:49]
	v_mfma_f32_16x16x32_bf16 v[50:53], v[144:147], v[172:175], v[50:53]
	v_mfma_f32_16x16x32_bf16 v[54:57], v[148:151], v[172:175], v[54:57]
	v_mfma_f32_16x16x32_bf16 v[58:61], v[152:155], v[172:175], v[58:61]
	v_mfma_f32_16x16x32_bf16 v[62:65], v[156:159], v[172:175], v[62:65]
	v_add_u32_e32 v176, 0x80, v176
	s_mov_b32 s16, 30
.Lg128_w2_loop:
	s_waitcnt lgkmcnt(0)
	v_mfma_f32_16x16x32_bf16 v[2:5], v[90:93], v[106:109], v[2:5]
	ds_read_b128 v[144:147], v142 offset:1024
	v_mfma_f32_16x16x32_bf16 v[6:9], v[94:97], v[106:109], v[6:9]
	ds_read_b128 v[148:151], v142 offset:3072
	v_mfma_f32_16x16x32_bf16 v[10:13], v[98:101], v[106:109], v[10:13]
	ds_read_b128 v[152:155], v142 offset:5120
	v_mfma_f32_16x16x32_bf16 v[14:17], v[102:105], v[106:109], v[14:17]
	ds_read_b128 v[156:159], v142 offset:7168
	v_mfma_f32_16x16x32_bf16 v[18:21], v[90:93], v[110:113], v[18:21]
	ds_read_b128 v[160:163], v141 offset:1024
	v_mfma_f32_16x16x32_bf16 v[22:25], v[94:97], v[110:113], v[22:25]
	ds_read_b128 v[164:167], v141 offset:3072
	v_mfma_f32_16x16x32_bf16 v[26:29], v[98:101], v[110:113], v[26:29]
	ds_read_b128 v[168:171], v141 offset:5120
	v_mfma_f32_16x16x32_bf16 v[30:33], v[102:105], v[110:113], v[30:33]
	ds_read_b128 v[172:175], v141 offset:7168
	v_mfma_f32_16x16x32_bf16 v[34:37], v[90:93], v[114:117], v[34:37]
	v_mfma_f32_16x16x32_bf16 v[38:41], v[94:97], v[114:117], v[38:41]
	v_mfma_f32_16x16x32_bf16 v[42:45], v[98:101], v[114:117], v[42:45]
	v_mfma_f32_16x16x32_bf16 v[46:49], v[102:105], v[114:117], v[46:49]
	v_mfma_f32_16x16x32_bf16 v[50:53], v[90:93], v[118:121], v[50:53]
	v_mfma_f32_16x16x32_bf16 v[54:57], v[94:97], v[118:121], v[54:57]
	v_mfma_f32_16x16x32_bf16 v[58:61], v[98:101], v[118:121], v[58:61]
	v_mfma_f32_16x16x32_bf16 v[62:65], v[102:105], v[118:121], v[62:65]
	s_waitcnt vmcnt(0) lgkmcnt(0)
	s_barrier
	v_mfma_f32_16x16x32_bf16 v[2:5], v[144:147], v[160:163], v[2:5]
	ds_read_b128 v[90:93], v142 offset:32768
	s_add_u32 m0, s22, 0x0
	v_mov_b32_e32 v179, v176
	global_load_lds_dwordx4 v179, s[6:7]
	v_mfma_f32_16x16x32_bf16 v[6:9], v[148:151], v[160:163], v[6:9]
	ds_read_b128 v[94:97], v142 offset:34816
	s_add_u32 m0, s22, 0x400
	v_add_u32_e32 v180, 0x40, v176
	global_load_lds_dwordx4 v180, s[6:7]
	v_mfma_f32_16x16x32_bf16 v[10:13], v[152:155], v[160:163], v[10:13]
	ds_read_b128 v[98:101], v142 offset:36864
	s_add_u32 m0, s22, 0x800
	v_add_u32_e32 v179, 0x20000, v176
	global_load_lds_dwordx4 v179, s[6:7]
	v_mfma_f32_16x16x32_bf16 v[14:17], v[156:159], v[160:163], v[14:17]
	ds_read_b128 v[102:105], v142 offset:38912
	s_add_u32 m0, s22, 0xc00
	v_add_u32_e32 v180, 0x20040, v176
	global_load_lds_dwordx4 v180, s[6:7]
	v_mfma_f32_16x16x32_bf16 v[18:21], v[144:147], v[164:167], v[18:21]
	ds_read_b128 v[106:109], v141 offset:32768
	s_add_u32 m0, s22, 0x4000
	v_mov_b32_e32 v179, v176
	global_load_lds_dwordx4 v179, s[8:9]
	v_mfma_f32_16x16x32_bf16 v[22:25], v[148:151], v[164:167], v[22:25]
	ds_read_b128 v[110:113], v141 offset:34816
	s_add_u32 m0, s22, 0x4400
	v_add_u32_e32 v180, 0x40, v176
	global_load_lds_dwordx4 v180, s[8:9]
	v_mfma_f32_16x16x32_bf16 v[26:29], v[152:155], v[164:167], v[26:29]
	ds_read_b128 v[114:117], v141 offset:36864
	s_add_u32 m0, s22, 0x4800
	v_add_u32_e32 v179, 0x20000, v176
	global_load_lds_dwordx4 v179, s[8:9]
	v_mfma_f32_16x16x32_bf16 v[30:33], v[156:159], v[164:167], v[30:33]
	ds_read_b128 v[118:121], v141 offset:38912
	s_add_u32 m0, s22, 0x4c00
	v_add_u32_e32 v180, 0x20040, v176
	global_load_lds_dwordx4 v180, s[8:9]
	v_mfma_f32_16x16x32_bf16 v[34:37], v[144:147], v[168:171], v[34:37]
	v_mfma_f32_16x16x32_bf16 v[38:41], v[148:151], v[168:171], v[38:41]
	v_mfma_f32_16x16x32_bf16 v[42:45], v[152:155], v[168:171], v[42:45]
	v_mfma_f32_16x16x32_bf16 v[46:49], v[156:159], v[168:171], v[46:49]
	v_mfma_f32_16x16x32_bf16 v[50:53], v[144:147], v[172:175], v[50:53]
	v_mfma_f32_16x16x32_bf16 v[54:57], v[148:151], v[172:175], v[54:57]
	v_mfma_f32_16x16x32_bf16 v[58:61], v[152:155], v[172:175], v[58:61]
	v_mfma_f32_16x16x32_bf16 v[62:65], v[156:159], v[172:175], v[62:65]
	v_add_u32_e32 v176, 0x80, v176
	s_waitcnt lgkmcnt(0)
	v_mfma_f32_16x16x32_bf16 v[2:5], v[90:93], v[106:109], v[2:5]
	ds_read_b128 v[144:147], v142 offset:33792
	v_mfma_f32_16x16x32_bf16 v[6:9], v[94:97], v[106:109], v[6:9]
	ds_read_b128 v[148:151], v142 offset:35840
	v_mfma_f32_16x16x32_bf16 v[10:13], v[98:101], v[106:109], v[10:13]
	ds_read_b128 v[152:155], v142 offset:37888
	v_mfma_f32_16x16x32_bf16 v[14:17], v[102:105], v[106:109], v[14:17]
	ds_read_b128 v[156:159], v142 offset:39936
	v_mfma_f32_16x16x32_bf16 v[18:21], v[90:93], v[110:113], v[18:21]
	ds_read_b128 v[160:163], v141 offset:33792
	v_mfma_f32_16x16x32_bf16 v[22:25], v[94:97], v[110:113], v[22:25]
	ds_read_b128 v[164:167], v141 offset:35840
	v_mfma_f32_16x16x32_bf16 v[26:29], v[98:101], v[110:113], v[26:29]
	ds_read_b128 v[168:171], v141 offset:37888
	v_mfma_f32_16x16x32_bf16 v[30:33], v[102:105], v[110:113], v[30:33]
	ds_read_b128 v[172:175], v141 offset:39936
	v_mfma_f32_16x16x32_bf16 v[34:37], v[90:93], v[114:117], v[34:37]
	v_mfma_f32_16x16x32_bf16 v[38:41], v[94:97], v[114:117], v[38:41]
	v_mfma_f32_16x16x32_bf16 v[42:45], v[98:101], v[114:117], v[42:45]
	v_mfma_f32_16x16x32_bf16 v[46:49], v[102:105], v[114:117], v[46:49]
	v_mfma_f32_16x16x32_bf16 v[50:53], v[90:93], v[118:121], v[50:53]
	v_mfma_f32_16x16x32_bf16 v[54:57], v[94:97], v[118:121], v[54:57]
	v_mfma_f32_16x16x32_bf16 v[58:61], v[98:101], v[118:121], v[58:61]
	v_mfma_f32_16x16x32_bf16 v[62:65], v[102:105], v[118:121], v[62:65]
	s_waitcnt vmcnt(0) lgkmcnt(0)
	s_barrier
	v_mfma_f32_16x16x32_bf16 v[2:5], v[144:147], v[160:163], v[2:5]
	ds_read_b128 v[90:93], v142
	s_add_u32 m0, s22, 0x8000
	v_mov_b32_e32 v179, v176
	global_load_lds_dwordx4 v179, s[6:7]
	v_mfma_f32_16x16x32_bf16 v[6:9], v[148:151], v[160:163], v[6:9]
	ds_read_b128 v[94:97], v142 offset:2048
	s_add_u32 m0, s22, 0x8400
	v_add_u32_e32 v180, 0x40, v176
	global_load_lds_dwordx4 v180, s[6:7]
	v_mfma_f32_16x16x32_bf16 v[10:13], v[152:155], v[160:163], v[10:13]
	ds_read_b128 v[98:101], v142 offset:4096
	s_add_u32 m0, s22, 0x8800
	v_add_u32_e32 v179, 0x20000, v176
	global_load_lds_dwordx4 v179, s[6:7]
	v_mfma_f32_16x16x32_bf16 v[14:17], v[156:159], v[160:163], v[14:17]
	ds_read_b128 v[102:105], v142 offset:6144
	s_add_u32 m0, s22, 0x8c00
	v_add_u32_e32 v180, 0x20040, v176
	global_load_lds_dwordx4 v180, s[6:7]
	v_mfma_f32_16x16x32_bf16 v[18:21], v[144:147], v[164:167], v[18:21]
	ds_read_b128 v[106:109], v141
	s_add_u32 m0, s22, 0xc000
	v_mov_b32_e32 v179, v176
	global_load_lds_dwordx4 v179, s[8:9]
	v_mfma_f32_16x16x32_bf16 v[22:25], v[148:151], v[164:167], v[22:25]
	ds_read_b128 v[110:113], v141 offset:2048
	s_add_u32 m0, s22, 0xc400
	v_add_u32_e32 v180, 0x40, v176
	global_load_lds_dwordx4 v180, s[8:9]
	v_mfma_f32_16x16x32_bf16 v[26:29], v[152:155], v[164:167], v[26:29]
	ds_read_b128 v[114:117], v141 offset:4096
	s_add_u32 m0, s22, 0xc800
	v_add_u32_e32 v179, 0x20000, v176
	global_load_lds_dwordx4 v179, s[8:9]
	v_mfma_f32_16x16x32_bf16 v[30:33], v[156:159], v[164:167], v[30:33]
	ds_read_b128 v[118:121], v141 offset:6144
	s_add_u32 m0, s22, 0xcc00
	v_add_u32_e32 v180, 0x20040, v176
	global_load_lds_dwordx4 v180, s[8:9]
	v_mfma_f32_16x16x32_bf16 v[34:37], v[144:147], v[168:171], v[34:37]
	v_mfma_f32_16x16x32_bf16 v[38:41], v[148:151], v[168:171], v[38:41]
	v_mfma_f32_16x16x32_bf16 v[42:45], v[152:155], v[168:171], v[42:45]
	v_mfma_f32_16x16x32_bf16 v[46:49], v[156:159], v[168:171], v[46:49]
	v_mfma_f32_16x16x32_bf16 v[50:53], v[144:147], v[172:175], v[50:53]
	v_mfma_f32_16x16x32_bf16 v[54:57], v[148:151], v[172:175], v[54:57]
	v_mfma_f32_16x16x32_bf16 v[58:61], v[152:155], v[172:175], v[58:61]
	v_mfma_f32_16x16x32_bf16 v[62:65], v[156:159], v[172:175], v[62:65]
	v_add_u32_e32 v176, 0x80, v176
	s_sub_u32 s16, s16, 1
	s_cmp_lg_u32 s16, 0
	s_cbranch_scc1 .Lg128_w2_loop
	s_add_u32 s12, s12, s83
.Lg128_w2_next_retry:
	s_cmp_ge_u32 s12, 128
	s_cbranch_scc1 .Lg128_w2_nonext
	s_lshr_b32 s3, s12, 6
	s_lshl_b32 s3, s3, 3
	s_add_u32 s3, s3, s65
	s_mov_b32 s17, s3
	s_mov_b32 s3, 0
	s_lshl_b32 s17, s17, 3
	s_bfe_u32 s23, s12, 0x30003
	s_add_u32 s13, s17, s23
	s_lshl_b32 s3, s3, 3
	s_and_b32 s23, s12, 7
	s_add_u32 s14, s3, s23
	s_lshl_b32 s13, s13, 7
	s_lshl_b32 s14, s14, 7
	s_lshl_b32 s3, s15, 5
	s_add_u32 s17, s3, s13
	s_mul_i32 s17, s17, 0x2000
	s_add_u32 s6, s18, s17
	s_addc_u32 s7, s19, 0
	s_add_u32 s17, s3, s14
	s_mul_i32 s17, s17, 0x2000
	s_add_u32 s8, s20, s17
	s_addc_u32 s9, s21, 0
	v_mov_b32_e32 v176, v177
	s_mov_b32 s16, 1
	s_waitcnt lgkmcnt(0)
	v_mfma_f32_16x16x32_bf16 v[2:5], v[90:93], v[106:109], v[2:5]
	ds_read_b128 v[144:147], v142 offset:1024
	v_mfma_f32_16x16x32_bf16 v[6:9], v[94:97], v[106:109], v[6:9]
	ds_read_b128 v[148:151], v142 offset:3072
	v_mfma_f32_16x16x32_bf16 v[10:13], v[98:101], v[106:109], v[10:13]
	ds_read_b128 v[152:155], v142 offset:5120
	v_mfma_f32_16x16x32_bf16 v[14:17], v[102:105], v[106:109], v[14:17]
	ds_read_b128 v[156:159], v142 offset:7168
	v_mfma_f32_16x16x32_bf16 v[18:21], v[90:93], v[110:113], v[18:21]
	ds_read_b128 v[160:163], v141 offset:1024
	v_mfma_f32_16x16x32_bf16 v[22:25], v[94:97], v[110:113], v[22:25]
	ds_read_b128 v[164:167], v141 offset:3072
	v_mfma_f32_16x16x32_bf16 v[26:29], v[98:101], v[110:113], v[26:29]
	ds_read_b128 v[168:171], v141 offset:5120
	v_mfma_f32_16x16x32_bf16 v[30:33], v[102:105], v[110:113], v[30:33]
	ds_read_b128 v[172:175], v141 offset:7168
	v_mfma_f32_16x16x32_bf16 v[34:37], v[90:93], v[114:117], v[34:37]
	v_mfma_f32_16x16x32_bf16 v[38:41], v[94:97], v[114:117], v[38:41]
	v_mfma_f32_16x16x32_bf16 v[42:45], v[98:101], v[114:117], v[42:45]
	v_mfma_f32_16x16x32_bf16 v[46:49], v[102:105], v[114:117], v[46:49]
	v_mfma_f32_16x16x32_bf16 v[50:53], v[90:93], v[118:121], v[50:53]
	v_mfma_f32_16x16x32_bf16 v[54:57], v[94:97], v[118:121], v[54:57]
	v_mfma_f32_16x16x32_bf16 v[58:61], v[98:101], v[118:121], v[58:61]
	v_mfma_f32_16x16x32_bf16 v[62:65], v[102:105], v[118:121], v[62:65]
	s_waitcnt vmcnt(0) lgkmcnt(0)
	s_barrier
	v_mfma_f32_16x16x32_bf16 v[2:5], v[144:147], v[160:163], v[2:5]
	ds_read_b128 v[90:93], v142 offset:32768
	s_add_u32 m0, s22, 0x0
	v_mov_b32_e32 v179, v176
	global_load_lds_dwordx4 v179, s[6:7]
	v_mfma_f32_16x16x32_bf16 v[6:9], v[148:151], v[160:163], v[6:9]
	ds_read_b128 v[94:97], v142 offset:34816
	s_add_u32 m0, s22, 0x400
	v_add_u32_e32 v180, 0x40, v176
	global_load_lds_dwordx4 v180, s[6:7]
	v_mfma_f32_16x16x32_bf16 v[10:13], v[152:155], v[160:163], v[10:13]
	ds_read_b128 v[98:101], v142 offset:36864
	s_add_u32 m0, s22, 0x800
	v_add_u32_e32 v179, 0x20000, v176
	global_load_lds_dwordx4 v179, s[6:7]
	v_mfma_f32_16x16x32_bf16 v[14:17], v[156:159], v[160:163], v[14:17]
	ds_read_b128 v[102:105], v142 offset:38912
	s_add_u32 m0, s22, 0xc00
	v_add_u32_e32 v180, 0x20040, v176
	global_load_lds_dwordx4 v180, s[6:7]
	v_mfma_f32_16x16x32_bf16 v[18:21], v[144:147], v[164:167], v[18:21]
	ds_read_b128 v[106:109], v141 offset:32768
	s_add_u32 m0, s22, 0x4000
	v_mov_b32_e32 v179, v176
	global_load_lds_dwordx4 v179, s[8:9]
	v_mfma_f32_16x16x32_bf16 v[22:25], v[148:151], v[164:167], v[22:25]
	ds_read_b128 v[110:113], v141 offset:34816
	s_add_u32 m0, s22, 0x4400
	v_add_u32_e32 v180, 0x40, v176
	global_load_lds_dwordx4 v180, s[8:9]
	v_mfma_f32_16x16x32_bf16 v[26:29], v[152:155], v[164:167], v[26:29]
	ds_read_b128 v[114:117], v141 offset:36864
	s_add_u32 m0, s22, 0x4800
	v_add_u32_e32 v179, 0x20000, v176
	global_load_lds_dwordx4 v179, s[8:9]
	v_mfma_f32_16x16x32_bf16 v[30:33], v[156:159], v[164:167], v[30:33]
	ds_read_b128 v[118:121], v141 offset:38912
	s_add_u32 m0, s22, 0x4c00
	v_add_u32_e32 v180, 0x20040, v176
	global_load_lds_dwordx4 v180, s[8:9]
	v_mfma_f32_16x16x32_bf16 v[34:37], v[144:147], v[168:171], v[34:37]
	v_mfma_f32_16x16x32_bf16 v[38:41], v[148:151], v[168:171], v[38:41]
	v_mfma_f32_16x16x32_bf16 v[42:45], v[152:155], v[168:171], v[42:45]
	v_mfma_f32_16x16x32_bf16 v[46:49], v[156:159], v[168:171], v[46:49]
	v_mfma_f32_16x16x32_bf16 v[50:53], v[144:147], v[172:175], v[50:53]
	v_mfma_f32_16x16x32_bf16 v[54:57], v[148:151], v[172:175], v[54:57]
	v_mfma_f32_16x16x32_bf16 v[58:61], v[152:155], v[172:175], v[58:61]
	v_mfma_f32_16x16x32_bf16 v[62:65], v[156:159], v[172:175], v[62:65]
	v_add_u32_e32 v176, 0x80, v176
	s_waitcnt lgkmcnt(0)
	v_mfma_f32_16x16x32_bf16 v[2:5], v[90:93], v[106:109], v[2:5]
	ds_read_b128 v[144:147], v142 offset:33792
	v_mfma_f32_16x16x32_bf16 v[6:9], v[94:97], v[106:109], v[6:9]
	ds_read_b128 v[148:151], v142 offset:35840
	v_mfma_f32_16x16x32_bf16 v[10:13], v[98:101], v[106:109], v[10:13]
	ds_read_b128 v[152:155], v142 offset:37888
	v_mfma_f32_16x16x32_bf16 v[14:17], v[102:105], v[106:109], v[14:17]
	ds_read_b128 v[156:159], v142 offset:39936
	v_mfma_f32_16x16x32_bf16 v[18:21], v[90:93], v[110:113], v[18:21]
	ds_read_b128 v[160:163], v141 offset:33792
	v_mfma_f32_16x16x32_bf16 v[22:25], v[94:97], v[110:113], v[22:25]
	ds_read_b128 v[164:167], v141 offset:35840
	v_mfma_f32_16x16x32_bf16 v[26:29], v[98:101], v[110:113], v[26:29]
	ds_read_b128 v[168:171], v141 offset:37888
	v_mfma_f32_16x16x32_bf16 v[30:33], v[102:105], v[110:113], v[30:33]
	ds_read_b128 v[172:175], v141 offset:39936
	v_mfma_f32_16x16x32_bf16 v[34:37], v[90:93], v[114:117], v[34:37]
	v_mfma_f32_16x16x32_bf16 v[38:41], v[94:97], v[114:117], v[38:41]
	v_mfma_f32_16x16x32_bf16 v[42:45], v[98:101], v[114:117], v[42:45]
	v_mfma_f32_16x16x32_bf16 v[46:49], v[102:105], v[114:117], v[46:49]
	v_mfma_f32_16x16x32_bf16 v[50:53], v[90:93], v[118:121], v[50:53]
	v_mfma_f32_16x16x32_bf16 v[54:57], v[94:97], v[118:121], v[54:57]
	v_mfma_f32_16x16x32_bf16 v[58:61], v[98:101], v[118:121], v[58:61]
	v_mfma_f32_16x16x32_bf16 v[62:65], v[102:105], v[118:121], v[62:65]
	s_waitcnt vmcnt(0) lgkmcnt(0)
	s_barrier
	v_mfma_f32_16x16x32_bf16 v[2:5], v[144:147], v[160:163], v[2:5]
	ds_read_b128 v[90:93], v142
	s_add_u32 m0, s22, 0x8000
	v_mov_b32_e32 v179, v176
	global_load_lds_dwordx4 v179, s[6:7]
	v_mfma_f32_16x16x32_bf16 v[6:9], v[148:151], v[160:163], v[6:9]
	ds_read_b128 v[94:97], v142 offset:2048
	s_add_u32 m0, s22, 0x8400
	v_add_u32_e32 v180, 0x40, v176
	global_load_lds_dwordx4 v180, s[6:7]
	v_mfma_f32_16x16x32_bf16 v[10:13], v[152:155], v[160:163], v[10:13]
	ds_read_b128 v[98:101], v142 offset:4096
	s_add_u32 m0, s22, 0x8800
	v_add_u32_e32 v179, 0x20000, v176
	global_load_lds_dwordx4 v179, s[6:7]
	v_mfma_f32_16x16x32_bf16 v[14:17], v[156:159], v[160:163], v[14:17]
	ds_read_b128 v[102:105], v142 offset:6144
	s_add_u32 m0, s22, 0x8c00
	v_add_u32_e32 v180, 0x20040, v176
	global_load_lds_dwordx4 v180, s[6:7]
	v_mfma_f32_16x16x32_bf16 v[18:21], v[144:147], v[164:167], v[18:21]
	ds_read_b128 v[106:109], v141
	s_add_u32 m0, s22, 0xc000
	v_mov_b32_e32 v179, v176
	global_load_lds_dwordx4 v179, s[8:9]
	v_mfma_f32_16x16x32_bf16 v[22:25], v[148:151], v[164:167], v[22:25]
	ds_read_b128 v[110:113], v141 offset:2048
	s_add_u32 m0, s22, 0xc400
	v_add_u32_e32 v180, 0x40, v176
	global_load_lds_dwordx4 v180, s[8:9]
	v_mfma_f32_16x16x32_bf16 v[26:29], v[152:155], v[164:167], v[26:29]
	ds_read_b128 v[114:117], v141 offset:4096
	s_add_u32 m0, s22, 0xc800
	v_add_u32_e32 v179, 0x20000, v176
	global_load_lds_dwordx4 v179, s[8:9]
	v_mfma_f32_16x16x32_bf16 v[30:33], v[156:159], v[164:167], v[30:33]
	ds_read_b128 v[118:121], v141 offset:6144
	s_add_u32 m0, s22, 0xcc00
	v_add_u32_e32 v180, 0x20040, v176
	global_load_lds_dwordx4 v180, s[8:9]
	v_mfma_f32_16x16x32_bf16 v[34:37], v[144:147], v[168:171], v[34:37]
	v_mfma_f32_16x16x32_bf16 v[38:41], v[148:151], v[168:171], v[38:41]
	v_mfma_f32_16x16x32_bf16 v[42:45], v[152:155], v[168:171], v[42:45]
	v_mfma_f32_16x16x32_bf16 v[46:49], v[156:159], v[168:171], v[46:49]
	v_mfma_f32_16x16x32_bf16 v[50:53], v[144:147], v[172:175], v[50:53]
	v_mfma_f32_16x16x32_bf16 v[54:57], v[148:151], v[172:175], v[54:57]
	v_mfma_f32_16x16x32_bf16 v[58:61], v[152:155], v[172:175], v[58:61]
	v_mfma_f32_16x16x32_bf16 v[62:65], v[156:159], v[172:175], v[62:65]
	v_add_u32_e32 v176, 0x80, v176
	s_branch .Lg128_w2_epi
.Lg128_w2_nonext:
	s_mov_b32 s16, 0
	s_waitcnt lgkmcnt(0)
	v_mfma_f32_16x16x32_bf16 v[2:5], v[90:93], v[106:109], v[2:5]
	ds_read_b128 v[144:147], v142 offset:1024
	v_mfma_f32_16x16x32_bf16 v[6:9], v[94:97], v[106:109], v[6:9]
	ds_read_b128 v[148:151], v142 offset:3072
	v_mfma_f32_16x16x32_bf16 v[10:13], v[98:101], v[106:109], v[10:13]
	ds_read_b128 v[152:155], v142 offset:5120
	v_mfma_f32_16x16x32_bf16 v[14:17], v[102:105], v[106:109], v[14:17]
	ds_read_b128 v[156:159], v142 offset:7168
	v_mfma_f32_16x16x32_bf16 v[18:21], v[90:93], v[110:113], v[18:21]
	ds_read_b128 v[160:163], v141 offset:1024
	v_mfma_f32_16x16x32_bf16 v[22:25], v[94:97], v[110:113], v[22:25]
	ds_read_b128 v[164:167], v141 offset:3072
	v_mfma_f32_16x16x32_bf16 v[26:29], v[98:101], v[110:113], v[26:29]
	ds_read_b128 v[168:171], v141 offset:5120
	v_mfma_f32_16x16x32_bf16 v[30:33], v[102:105], v[110:113], v[30:33]
	ds_read_b128 v[172:175], v141 offset:7168
	v_mfma_f32_16x16x32_bf16 v[34:37], v[90:93], v[114:117], v[34:37]
	v_mfma_f32_16x16x32_bf16 v[38:41], v[94:97], v[114:117], v[38:41]
	v_mfma_f32_16x16x32_bf16 v[42:45], v[98:101], v[114:117], v[42:45]
	v_mfma_f32_16x16x32_bf16 v[46:49], v[102:105], v[114:117], v[46:49]
	v_mfma_f32_16x16x32_bf16 v[50:53], v[90:93], v[118:121], v[50:53]
	v_mfma_f32_16x16x32_bf16 v[54:57], v[94:97], v[118:121], v[54:57]
	v_mfma_f32_16x16x32_bf16 v[58:61], v[98:101], v[118:121], v[58:61]
	v_mfma_f32_16x16x32_bf16 v[62:65], v[102:105], v[118:121], v[62:65]
	s_waitcnt vmcnt(0) lgkmcnt(0)
	s_barrier
	v_mfma_f32_16x16x32_bf16 v[2:5], v[144:147], v[160:163], v[2:5]
	ds_read_b128 v[90:93], v142 offset:32768
	v_mfma_f32_16x16x32_bf16 v[6:9], v[148:151], v[160:163], v[6:9]
	ds_read_b128 v[94:97], v142 offset:34816
	v_mfma_f32_16x16x32_bf16 v[10:13], v[152:155], v[160:163], v[10:13]
	ds_read_b128 v[98:101], v142 offset:36864
	v_mfma_f32_16x16x32_bf16 v[14:17], v[156:159], v[160:163], v[14:17]
	ds_read_b128 v[102:105], v142 offset:38912
	v_mfma_f32_16x16x32_bf16 v[18:21], v[144:147], v[164:167], v[18:21]
	ds_read_b128 v[106:109], v141 offset:32768
	v_mfma_f32_16x16x32_bf16 v[22:25], v[148:151], v[164:167], v[22:25]
	ds_read_b128 v[110:113], v141 offset:34816
	v_mfma_f32_16x16x32_bf16 v[26:29], v[152:155], v[164:167], v[26:29]
	ds_read_b128 v[114:117], v141 offset:36864
	v_mfma_f32_16x16x32_bf16 v[30:33], v[156:159], v[164:167], v[30:33]
	ds_read_b128 v[118:121], v141 offset:38912
	v_mfma_f32_16x16x32_bf16 v[34:37], v[144:147], v[168:171], v[34:37]
	v_mfma_f32_16x16x32_bf16 v[38:41], v[148:151], v[168:171], v[38:41]
	v_mfma_f32_16x16x32_bf16 v[42:45], v[152:155], v[168:171], v[42:45]
	v_mfma_f32_16x16x32_bf16 v[46:49], v[156:159], v[168:171], v[46:49]
	v_mfma_f32_16x16x32_bf16 v[50:53], v[144:147], v[172:175], v[50:53]
	v_mfma_f32_16x16x32_bf16 v[54:57], v[148:151], v[172:175], v[54:57]
	v_mfma_f32_16x16x32_bf16 v[58:61], v[152:155], v[172:175], v[58:61]
	v_mfma_f32_16x16x32_bf16 v[62:65], v[156:159], v[172:175], v[62:65]
	s_waitcnt lgkmcnt(0)
	v_mfma_f32_16x16x32_bf16 v[2:5], v[90:93], v[106:109], v[2:5]
	ds_read_b128 v[144:147], v142 offset:33792
	v_mfma_f32_16x16x32_bf16 v[6:9], v[94:97], v[106:109], v[6:9]
	ds_read_b128 v[148:151], v142 offset:35840
	v_mfma_f32_16x16x32_bf16 v[10:13], v[98:101], v[106:109], v[10:13]
	ds_read_b128 v[152:155], v142 offset:37888
	v_mfma_f32_16x16x32_bf16 v[14:17], v[102:105], v[106:109], v[14:17]
	ds_read_b128 v[156:159], v142 offset:39936
	v_mfma_f32_16x16x32_bf16 v[18:21], v[90:93], v[110:113], v[18:21]
	ds_read_b128 v[160:163], v141 offset:33792
	v_mfma_f32_16x16x32_bf16 v[22:25], v[94:97], v[110:113], v[22:25]
	ds_read_b128 v[164:167], v141 offset:35840
	v_mfma_f32_16x16x32_bf16 v[26:29], v[98:101], v[110:113], v[26:29]
	ds_read_b128 v[168:171], v141 offset:37888
	v_mfma_f32_16x16x32_bf16 v[30:33], v[102:105], v[110:113], v[30:33]
	ds_read_b128 v[172:175], v141 offset:39936
	v_mfma_f32_16x16x32_bf16 v[34:37], v[90:93], v[114:117], v[34:37]
	v_mfma_f32_16x16x32_bf16 v[38:41], v[94:97], v[114:117], v[38:41]
	v_mfma_f32_16x16x32_bf16 v[42:45], v[98:101], v[114:117], v[42:45]
	v_mfma_f32_16x16x32_bf16 v[46:49], v[102:105], v[114:117], v[46:49]
	v_mfma_f32_16x16x32_bf16 v[50:53], v[90:93], v[118:121], v[50:53]
	v_mfma_f32_16x16x32_bf16 v[54:57], v[94:97], v[118:121], v[54:57]
	v_mfma_f32_16x16x32_bf16 v[58:61], v[98:101], v[118:121], v[58:61]
	v_mfma_f32_16x16x32_bf16 v[62:65], v[102:105], v[118:121], v[62:65]
	s_waitcnt vmcnt(0) lgkmcnt(0)
	s_barrier
	v_mfma_f32_16x16x32_bf16 v[2:5], v[144:147], v[160:163], v[2:5]
	v_mfma_f32_16x16x32_bf16 v[6:9], v[148:151], v[160:163], v[6:9]
	v_mfma_f32_16x16x32_bf16 v[10:13], v[152:155], v[160:163], v[10:13]
	v_mfma_f32_16x16x32_bf16 v[14:17], v[156:159], v[160:163], v[14:17]
	v_mfma_f32_16x16x32_bf16 v[18:21], v[144:147], v[164:167], v[18:21]
	v_mfma_f32_16x16x32_bf16 v[22:25], v[148:151], v[164:167], v[22:25]
	v_mfma_f32_16x16x32_bf16 v[26:29], v[152:155], v[164:167], v[26:29]
	v_mfma_f32_16x16x32_bf16 v[30:33], v[156:159], v[164:167], v[30:33]
	v_mfma_f32_16x16x32_bf16 v[34:37], v[144:147], v[168:171], v[34:37]
	v_mfma_f32_16x16x32_bf16 v[38:41], v[148:151], v[168:171], v[38:41]
	v_mfma_f32_16x16x32_bf16 v[42:45], v[152:155], v[168:171], v[42:45]
	v_mfma_f32_16x16x32_bf16 v[46:49], v[156:159], v[168:171], v[46:49]
	v_mfma_f32_16x16x32_bf16 v[50:53], v[144:147], v[172:175], v[50:53]
	v_mfma_f32_16x16x32_bf16 v[54:57], v[148:151], v[172:175], v[54:57]
	v_mfma_f32_16x16x32_bf16 v[58:61], v[152:155], v[172:175], v[58:61]
	v_mfma_f32_16x16x32_bf16 v[62:65], v[156:159], v[172:175], v[62:65]
.Lg128_w2_epi:
	global_load_dwordx4 v[196:199], v181, s[4:5]
	global_load_dwordx4 v[200:203], v181, s[4:5] offset:64
	global_load_dwordx4 v[204:207], v181, s[4:5] offset:128
	global_load_dwordx4 v[212:215], v181, s[4:5] offset:192
	global_load_dwordx4 v[66:69], v178, s[26:27]
	global_load_dwordx4 v[70:73], v178, s[26:27] offset:64
	global_load_dwordx4 v[74:77], v178, s[26:27] offset:128
	global_load_dwordx4 v[78:81], v178, s[26:27] offset:192
	v_add_u32_e32 v180, 0x10000, v178
	global_load_dwordx4 v[82:85], v180, s[26:27]
	global_load_dwordx4 v[86:89], v180, s[26:27] offset:64
	global_load_dwordx4 v[122:125], v180, s[26:27] offset:128
	global_load_dwordx4 v[126:129], v180, s[26:27] offset:192
	s_waitcnt vmcnt(0)
	v_pk_fma_f32 v[2:3], v[196:197], v[2:3], v[66:67]
	v_pk_fma_f32 v[4:5], v[198:199], v[4:5], v[68:69]
	v_pk_fma_f32 v[6:7], v[200:201], v[6:7], v[70:71]
	v_pk_fma_f32 v[8:9], v[202:203], v[8:9], v[72:73]
	v_pk_fma_f32 v[10:11], v[204:205], v[10:11], v[74:75]
	v_pk_fma_f32 v[12:13], v[206:207], v[12:13], v[76:77]
	v_pk_fma_f32 v[14:15], v[212:213], v[14:15], v[78:79]
	v_pk_fma_f32 v[16:17], v[214:215], v[16:17], v[80:81]
	v_pk_fma_f32 v[18:19], v[196:197], v[18:19], v[82:83]
	v_pk_fma_f32 v[20:21], v[198:199], v[20:21], v[84:85]
	v_pk_fma_f32 v[22:23], v[200:201], v[22:23], v[86:87]
	v_pk_fma_f32 v[24:25], v[202:203], v[24:25], v[88:89]
	v_pk_fma_f32 v[26:27], v[204:205], v[26:27], v[122:123]
	v_pk_fma_f32 v[28:29], v[206:207], v[28:29], v[124:125]
	v_pk_fma_f32 v[30:31], v[212:213], v[30:31], v[126:127]
	v_pk_fma_f32 v[32:33], v[214:215], v[32:33], v[128:129]
	v_add_u32_e32 v179, 0x20000, v178
	global_load_dwordx4 v[66:69], v179, s[26:27]
	global_load_dwordx4 v[70:73], v179, s[26:27] offset:64
	global_load_dwordx4 v[74:77], v179, s[26:27] offset:128
	global_load_dwordx4 v[78:81], v179, s[26:27] offset:192
	v_add_u32_e32 v180, 0x30000, v178
	global_load_dwordx4 v[82:85], v180, s[26:27]
	global_load_dwordx4 v[86:89], v180, s[26:27] offset:64
	global_load_dwordx4 v[122:125], v180, s[26:27] offset:128
	global_load_dwordx4 v[126:129], v180, s[26:27] offset:192
	global_store_dwordx4 v178, v[2:5], s[10:11]
	global_store_dwordx4 v178, v[6:9], s[10:11] offset:64
	global_store_dwordx4 v178, v[10:13], s[10:11] offset:128
	global_store_dwordx4 v178, v[14:17], s[10:11] offset:192
	v_add_u32_e32 v180, 0x10000, v178
	global_store_dwordx4 v180, v[18:21], s[10:11]
	global_store_dwordx4 v180, v[22:25], s[10:11] offset:64
	global_store_dwordx4 v180, v[26:29], s[10:11] offset:128
	global_store_dwordx4 v180, v[30:33], s[10:11] offset:192
	s_waitcnt vmcnt(8)
	v_pk_fma_f32 v[34:35], v[196:197], v[34:35], v[66:67]
	v_pk_fma_f32 v[36:37], v[198:199], v[36:37], v[68:69]
	v_pk_fma_f32 v[38:39], v[200:201], v[38:39], v[70:71]
	v_pk_fma_f32 v[40:41], v[202:203], v[40:41], v[72:73]
	v_pk_fma_f32 v[42:43], v[204:205], v[42:43], v[74:75]
	v_pk_fma_f32 v[44:45], v[206:207], v[44:45], v[76:77]
	v_pk_fma_f32 v[46:47], v[212:213], v[46:47], v[78:79]
	v_pk_fma_f32 v[48:49], v[214:215], v[48:49], v[80:81]
	v_pk_fma_f32 v[50:51], v[196:197], v[50:51], v[82:83]
	v_pk_fma_f32 v[52:53], v[198:199], v[52:53], v[84:85]
	v_pk_fma_f32 v[54:55], v[200:201], v[54:55], v[86:87]
	v_pk_fma_f32 v[56:57], v[202:203], v[56:57], v[88:89]
	v_pk_fma_f32 v[58:59], v[204:205], v[58:59], v[122:123]
	v_pk_fma_f32 v[60:61], v[206:207], v[60:61], v[124:125]
	v_pk_fma_f32 v[62:63], v[212:213], v[62:63], v[126:127]
	v_pk_fma_f32 v[64:65], v[214:215], v[64:65], v[128:129]
	v_add_u32_e32 v179, 0x20000, v178
	global_store_dwordx4 v179, v[34:37], s[10:11]
	global_store_dwordx4 v179, v[38:41], s[10:11] offset:64
	global_store_dwordx4 v179, v[42:45], s[10:11] offset:128
	global_store_dwordx4 v179, v[46:49], s[10:11] offset:192
	v_add_u32_e32 v180, 0x30000, v178
	global_store_dwordx4 v180, v[50:53], s[10:11]
	global_store_dwordx4 v180, v[54:57], s[10:11] offset:64
	global_store_dwordx4 v180, v[58:61], s[10:11] offset:128
	global_store_dwordx4 v180, v[62:65], s[10:11] offset:192
	s_cmp_lg_u32 s16, 0
	s_cbranch_scc1 .Lg128_w2_tile
.Lg128_w2_done:
.LBB0_30:
	s_mov_b64 s[4:5], 0

.LBB0_39:
.LBB0_40:
	v_readlane_b32 s4, v239, 5
	v_readlane_b32 s5, v239, 6
	s_andn2_b64 vcc, exec, s[4:5]
	s_cbranch_vccnz .LBB0_45
	s_load_dwordx2 s[4:5], s[0:1], 0x130
	v_and_b32_e32 v0, 63, v133
	v_lshrrev_b32_e32 v131, 6, v133
	v_lshrrev_b32_e32 v195, 2, v0
	v_readfirstlane_b32 s15, v131
	v_mul_u32_u24_e32 v177, 0x800, v195
	v_and_b32_e32 v195, 3, v0
	v_lshlrev_b32_e32 v195, 4, v195
	v_lshrrev_b32_e32 v131, 5, v0
	v_lshlrev_b32_e32 v131, 5, v131
	v_xor_b32_e32 v195, v195, v131
	v_add_u32_e32 v177, v177, v195
	v_and_b32_e32 v195, 15, v0
	v_lshrrev_b32_e32 v131, 4, v0
	v_lshlrev_b32_e32 v141, 6, v195
	v_lshl_or_b32 v141, v131, 4, v141
	v_and_b32_e32 v178, 8, v0
	v_lshlrev_b32_e32 v178, 2, v178
	v_xor_b32_e32 v141, v141, v178
	v_mul_u32_u24_e32 v178, 0x2000, v195
	v_lshl_or_b32 v178, v131, 3, v178
	s_waitcnt lgkmcnt(0)
	s_add_u32 s18, s4, 0x2b27800
	s_addc_u32 s19, s5, 0
	s_add_u32 s20, s4, 0x1b27800
	s_addc_u32 s21, s5, 0
	s_add_u32 s24, s4, 0x4b27800
	s_addc_u32 s25, s5, 0
	s_and_b32 s3, s15, 1
	s_lshl_b32 s3, s3, 13
	s_add_u32 s3, s3, 16384
	v_add_u32_e32 v142, s3, v141
	s_lshr_b32 s3, s15, 1
	s_lshl_b32 s3, s3, 13
	v_add_u32_e32 v141, s3, v141
	s_lshl_b32 s22, s15, 12
	s_mov_b32 s12, s79
.Lg128_w1_first_retry:
	s_cmp_ge_u32 s12, 512
	s_cbranch_scc1 .Lg128_w1_done
	s_lshr_b32 s3, s12, 6
	s_lshl_b32 s3, s3, 3
	s_add_u32 s3, s3, s65
	s_lshr_b32 s17, s3, 2
	s_and_b32 s3, s3, 3
	s_lshl_b32 s17, s17, 3
	s_bfe_u32 s23, s12, 0x30003
	s_add_u32 s13, s17, s23
	s_lshl_b32 s3, s3, 3
	s_and_b32 s23, s12, 7
	s_add_u32 s14, s3, s23
	s_lshl_b32 s13, s13, 7
	s_lshl_b32 s14, s14, 7
	s_lshl_b32 s3, s15, 5
	s_add_u32 s17, s3, s13
	s_mul_i32 s17, s17, 0x800
	s_add_u32 s6, s18, s17
	s_addc_u32 s7, s19, 0
	s_add_u32 s17, s3, s14
	s_mul_i32 s17, s17, 0x800
	s_add_u32 s8, s20, s17
	s_addc_u32 s9, s21, 0
	s_barrier
	v_mov_b32_e32 v176, v177
	s_add_u32 m0, s22, 0x0
	v_mov_b32_e32 v179, v176
	global_load_lds_dwordx4 v179, s[6:7]
	s_add_u32 m0, s22, 0x400
	v_add_u32_e32 v180, 0x40, v176
	global_load_lds_dwordx4 v180, s[6:7]
	s_add_u32 m0, s22, 0x800
	v_add_u32_e32 v179, 0x8000, v176
	global_load_lds_dwordx4 v179, s[6:7]
	s_add_u32 m0, s22, 0xc00
	v_add_u32_e32 v180, 0x8040, v176
	global_load_lds_dwordx4 v180, s[6:7]
	s_add_u32 m0, s22, 0x4000
	v_mov_b32_e32 v179, v176
	global_load_lds_dwordx4 v179, s[8:9]
	s_add_u32 m0, s22, 0x4400
	v_add_u32_e32 v180, 0x40, v176
	global_load_lds_dwordx4 v180, s[8:9]
	s_add_u32 m0, s22, 0x4800
	v_add_u32_e32 v179, 0x8000, v176
	global_load_lds_dwordx4 v179, s[8:9]
	s_add_u32 m0, s22, 0x4c00
	v_add_u32_e32 v180, 0x8040, v176
	global_load_lds_dwordx4 v180, s[8:9]
	v_add_u32_e32 v176, 0x80, v176
	s_add_u32 m0, s22, 0x8000
	v_mov_b32_e32 v179, v176
	global_load_lds_dwordx4 v179, s[6:7]
	s_add_u32 m0, s22, 0x8400
	v_add_u32_e32 v180, 0x40, v176
	global_load_lds_dwordx4 v180, s[6:7]
	s_add_u32 m0, s22, 0x8800
	v_add_u32_e32 v179, 0x8000, v176
	global_load_lds_dwordx4 v179, s[6:7]
	s_add_u32 m0, s22, 0x8c00
	v_add_u32_e32 v180, 0x8040, v176
	global_load_lds_dwordx4 v180, s[6:7]
	s_add_u32 m0, s22, 0xc000
	v_mov_b32_e32 v179, v176
	global_load_lds_dwordx4 v179, s[8:9]
	s_add_u32 m0, s22, 0xc400
	v_add_u32_e32 v180, 0x40, v176
	global_load_lds_dwordx4 v180, s[8:9]
	s_add_u32 m0, s22, 0xc800
	v_add_u32_e32 v179, 0x8000, v176
	global_load_lds_dwordx4 v179, s[8:9]
	s_add_u32 m0, s22, 0xcc00
	v_add_u32_e32 v180, 0x8040, v176
	global_load_lds_dwordx4 v180, s[8:9]
	v_add_u32_e32 v176, 0x80, v176
	s_waitcnt vmcnt(0)
	s_barrier
	ds_read_b128 v[90:93], v142
	ds_read_b128 v[94:97], v142 offset:2048
	ds_read_b128 v[98:101], v142 offset:4096
	ds_read_b128 v[102:105], v142 offset:6144
	ds_read_b128 v[106:109], v141
	ds_read_b128 v[110:113], v141 offset:2048
	ds_read_b128 v[114:117], v141 offset:4096
	ds_read_b128 v[118:121], v141 offset:6144
.Lg128_w1_tile:
	s_lshr_b32 s3, s15, 1
	s_lshl_b32 s3, s3, 6
	s_add_u32 s3, s3, s13
	s_mul_i32 s17, s3, 0x2000
	s_and_b32 s3, s15, 1
	s_lshl_b32 s3, s3, 6
	s_add_u32 s3, s3, s14
	s_mul_i32 s3, s3, 2
	s_add_u32 s17, s17, s3
	s_add_u32 s10, s24, s17
	s_addc_u32 s11, s25, 0
	s_waitcnt lgkmcnt(0)
	v_mfma_f32_16x16x32_bf16 v[2:5], v[90:93], v[106:109], 0
	ds_read_b128 v[144:147], v142 offset:1024
	v_mfma_f32_16x16x32_bf16 v[6:9], v[94:97], v[106:109], 0
	ds_read_b128 v[148:151], v142 offset:3072
	v_mfma_f32_16x16x32_bf16 v[10:13], v[98:101], v[106:109], 0
	ds_read_b128 v[152:155], v142 offset:5120
	v_mfma_f32_16x16x32_bf16 v[14:17], v[102:105], v[106:109], 0
	ds_read_b128 v[156:159], v142 offset:7168
	v_mfma_f32_16x16x32_bf16 v[18:21], v[90:93], v[110:113], 0
	ds_read_b128 v[160:163], v141 offset:1024
	v_mfma_f32_16x16x32_bf16 v[22:25], v[94:97], v[110:113], 0
	ds_read_b128 v[164:167], v141 offset:3072
	v_mfma_f32_16x16x32_bf16 v[26:29], v[98:101], v[110:113], 0
	ds_read_b128 v[168:171], v141 offset:5120
	v_mfma_f32_16x16x32_bf16 v[30:33], v[102:105], v[110:113], 0
	ds_read_b128 v[172:175], v141 offset:7168
	v_mfma_f32_16x16x32_bf16 v[34:37], v[90:93], v[114:117], 0
	v_mfma_f32_16x16x32_bf16 v[38:41], v[94:97], v[114:117], 0
	v_mfma_f32_16x16x32_bf16 v[42:45], v[98:101], v[114:117], 0
	v_mfma_f32_16x16x32_bf16 v[46:49], v[102:105], v[114:117], 0
	v_mfma_f32_16x16x32_bf16 v[50:53], v[90:93], v[118:121], 0
	v_mfma_f32_16x16x32_bf16 v[54:57], v[94:97], v[118:121], 0
	v_mfma_f32_16x16x32_bf16 v[58:61], v[98:101], v[118:121], 0
	v_mfma_f32_16x16x32_bf16 v[62:65], v[102:105], v[118:121], 0
	s_waitcnt vmcnt(16) lgkmcnt(0)
	s_barrier
	v_mfma_f32_16x16x32_bf16 v[2:5], v[144:147], v[160:163], v[2:5]
	ds_read_b128 v[90:93], v142 offset:32768
	s_add_u32 m0, s22, 0x0
	v_mov_b32_e32 v179, v176
	global_load_lds_dwordx4 v179, s[6:7]
	v_mfma_f32_16x16x32_bf16 v[6:9], v[148:151], v[160:163], v[6:9]
	ds_read_b128 v[94:97], v142 offset:34816
	s_add_u32 m0, s22, 0x400
	v_add_u32_e32 v180, 0x40, v176
	global_load_lds_dwordx4 v180, s[6:7]
	v_mfma_f32_16x16x32_bf16 v[10:13], v[152:155], v[160:163], v[10:13]
	ds_read_b128 v[98:101], v142 offset:36864
	s_add_u32 m0, s22, 0x800
	v_add_u32_e32 v179, 0x8000, v176
	global_load_lds_dwordx4 v179, s[6:7]
	v_mfma_f32_16x16x32_bf16 v[14:17], v[156:159], v[160:163], v[14:17]
	ds_read_b128 v[102:105], v142 offset:38912
	s_add_u32 m0, s22, 0xc00
	v_add_u32_e32 v180, 0x8040, v176
	global_load_lds_dwordx4 v180, s[6:7]
	v_mfma_f32_16x16x32_bf16 v[18:21], v[144:147], v[164:167], v[18:21]
	ds_read_b128 v[106:109], v141 offset:32768
	s_add_u32 m0, s22, 0x4000
	v_mov_b32_e32 v179, v176
	global_load_lds_dwordx4 v179, s[8:9]
	v_mfma_f32_16x16x32_bf16 v[22:25], v[148:151], v[164:167], v[22:25]
	ds_read_b128 v[110:113], v141 offset:34816
	s_add_u32 m0, s22, 0x4400
	v_add_u32_e32 v180, 0x40, v176
	global_load_lds_dwordx4 v180, s[8:9]
	v_mfma_f32_16x16x32_bf16 v[26:29], v[152:155], v[164:167], v[26:29]
	ds_read_b128 v[114:117], v141 offset:36864
	s_add_u32 m0, s22, 0x4800
	v_add_u32_e32 v179, 0x8000, v176
	global_load_lds_dwordx4 v179, s[8:9]
	v_mfma_f32_16x16x32_bf16 v[30:33], v[156:159], v[164:167], v[30:33]
	ds_read_b128 v[118:121], v141 offset:38912
	s_add_u32 m0, s22, 0x4c00
	v_add_u32_e32 v180, 0x8040, v176
	global_load_lds_dwordx4 v180, s[8:9]
	v_mfma_f32_16x16x32_bf16 v[34:37], v[144:147], v[168:171], v[34:37]
	v_mfma_f32_16x16x32_bf16 v[38:41], v[148:151], v[168:171], v[38:41]
	v_mfma_f32_16x16x32_bf16 v[42:45], v[152:155], v[168:171], v[42:45]
	v_mfma_f32_16x16x32_bf16 v[46:49], v[156:159], v[168:171], v[46:49]
	v_mfma_f32_16x16x32_bf16 v[50:53], v[144:147], v[172:175], v[50:53]
	v_mfma_f32_16x16x32_bf16 v[54:57], v[148:151], v[172:175], v[54:57]
	v_mfma_f32_16x16x32_bf16 v[58:61], v[152:155], v[172:175], v[58:61]
	v_mfma_f32_16x16x32_bf16 v[62:65], v[156:159], v[172:175], v[62:65]
	v_add_u32_e32 v176, 0x80, v176
	s_waitcnt lgkmcnt(0)
	v_mfma_f32_16x16x32_bf16 v[2:5], v[90:93], v[106:109], v[2:5]
	ds_read_b128 v[144:147], v142 offset:33792
	v_mfma_f32_16x16x32_bf16 v[6:9], v[94:97], v[106:109], v[6:9]
	ds_read_b128 v[148:151], v142 offset:35840
	v_mfma_f32_16x16x32_bf16 v[10:13], v[98:101], v[106:109], v[10:13]
	ds_read_b128 v[152:155], v142 offset:37888
	v_mfma_f32_16x16x32_bf16 v[14:17], v[102:105], v[106:109], v[14:17]
	ds_read_b128 v[156:159], v142 offset:39936
	v_mfma_f32_16x16x32_bf16 v[18:21], v[90:93], v[110:113], v[18:21]
	ds_read_b128 v[160:163], v141 offset:33792
	v_mfma_f32_16x16x32_bf16 v[22:25], v[94:97], v[110:113], v[22:25]
	ds_read_b128 v[164:167], v141 offset:35840
	v_mfma_f32_16x16x32_bf16 v[26:29], v[98:101], v[110:113], v[26:29]
	ds_read_b128 v[168:171], v141 offset:37888
	v_mfma_f32_16x16x32_bf16 v[30:33], v[102:105], v[110:113], v[30:33]
	ds_read_b128 v[172:175], v141 offset:39936
	v_mfma_f32_16x16x32_bf16 v[34:37], v[90:93], v[114:117], v[34:37]
	v_mfma_f32_16x16x32_bf16 v[38:41], v[94:97], v[114:117], v[38:41]
	v_mfma_f32_16x16x32_bf16 v[42:45], v[98:101], v[114:117], v[42:45]
	v_mfma_f32_16x16x32_bf16 v[46:49], v[102:105], v[114:117], v[46:49]
	v_mfma_f32_16x16x32_bf16 v[50:53], v[90:93], v[118:121], v[50:53]
	v_mfma_f32_16x16x32_bf16 v[54:57], v[94:97], v[118:121], v[54:57]
	v_mfma_f32_16x16x32_bf16 v[58:61], v[98:101], v[118:121], v[58:61]
	v_mfma_f32_16x16x32_bf16 v[62:65], v[102:105], v[118:121], v[62:65]
	s_waitcnt vmcnt(0) lgkmcnt(0)
	s_barrier
	v_mfma_f32_16x16x32_bf16 v[2:5], v[144:147], v[160:163], v[2:5]
	ds_read_b128 v[90:93], v142
	s_add_u32 m0, s22, 0x8000
	v_mov_b32_e32 v179, v176
	global_load_lds_dwordx4 v179, s[6:7]
	v_mfma_f32_16x16x32_bf16 v[6:9], v[148:151], v[160:163], v[6:9]
	ds_read_b128 v[94:97], v142 offset:2048
	s_add_u32 m0, s22, 0x8400
	v_add_u32_e32 v180, 0x40, v176
	global_load_lds_dwordx4 v180, s[6:7]
	v_mfma_f32_16x16x32_bf16 v[10:13], v[152:155], v[160:163], v[10:13]
	ds_read_b128 v[98:101], v142 offset:4096
	s_add_u32 m0, s22, 0x8800
	v_add_u32_e32 v179, 0x8000, v176
	global_load_lds_dwordx4 v179, s[6:7]
	v_mfma_f32_16x16x32_bf16 v[14:17], v[156:159], v[160:163], v[14:17]
	ds_read_b128 v[102:105], v142 offset:6144
	s_add_u32 m0, s22, 0x8c00
	v_add_u32_e32 v180, 0x8040, v176
	global_load_lds_dwordx4 v180, s[6:7]
	v_mfma_f32_16x16x32_bf16 v[18:21], v[144:147], v[164:167], v[18:21]
	ds_read_b128 v[106:109], v141
	s_add_u32 m0, s22, 0xc000
	v_mov_b32_e32 v179, v176
	global_load_lds_dwordx4 v179, s[8:9]
	v_mfma_f32_16x16x32_bf16 v[22:25], v[148:151], v[164:167], v[22:25]
	ds_read_b128 v[110:113], v141 offset:2048
	s_add_u32 m0, s22, 0xc400
	v_add_u32_e32 v180, 0x40, v176
	global_load_lds_dwordx4 v180, s[8:9]
	v_mfma_f32_16x16x32_bf16 v[26:29], v[152:155], v[164:167], v[26:29]
	ds_read_b128 v[114:117], v141 offset:4096
	s_add_u32 m0, s22, 0xc800
	v_add_u32_e32 v179, 0x8000, v176
	global_load_lds_dwordx4 v179, s[8:9]
	v_mfma_f32_16x16x32_bf16 v[30:33], v[156:159], v[164:167], v[30:33]
	ds_read_b128 v[118:121], v141 offset:6144
	s_add_u32 m0, s22, 0xcc00
	v_add_u32_e32 v180, 0x8040, v176
	global_load_lds_dwordx4 v180, s[8:9]
	v_mfma_f32_16x16x32_bf16 v[34:37], v[144:147], v[168:171], v[34:37]
	v_mfma_f32_16x16x32_bf16 v[38:41], v[148:151], v[168:171], v[38:41]
	v_mfma_f32_16x16x32_bf16 v[42:45], v[152:155], v[168:171], v[42:45]
	v_mfma_f32_16x16x32_bf16 v[46:49], v[156:159], v[168:171], v[46:49]
	v_mfma_f32_16x16x32_bf16 v[50:53], v[144:147], v[172:175], v[50:53]
	v_mfma_f32_16x16x32_bf16 v[54:57], v[148:151], v[172:175], v[54:57]
	v_mfma_f32_16x16x32_bf16 v[58:61], v[152:155], v[172:175], v[58:61]
	v_mfma_f32_16x16x32_bf16 v[62:65], v[156:159], v[172:175], v[62:65]
	v_add_u32_e32 v176, 0x80, v176
	s_mov_b32 s16, 6
.Lg128_w1_loop:
	s_waitcnt lgkmcnt(0)
	v_mfma_f32_16x16x32_bf16 v[2:5], v[90:93], v[106:109], v[2:5]
	ds_read_b128 v[144:147], v142 offset:1024
	v_mfma_f32_16x16x32_bf16 v[6:9], v[94:97], v[106:109], v[6:9]
	ds_read_b128 v[148:151], v142 offset:3072
	v_mfma_f32_16x16x32_bf16 v[10:13], v[98:101], v[106:109], v[10:13]
	ds_read_b128 v[152:155], v142 offset:5120
	v_mfma_f32_16x16x32_bf16 v[14:17], v[102:105], v[106:109], v[14:17]
	ds_read_b128 v[156:159], v142 offset:7168
	v_mfma_f32_16x16x32_bf16 v[18:21], v[90:93], v[110:113], v[18:21]
	ds_read_b128 v[160:163], v141 offset:1024
	v_mfma_f32_16x16x32_bf16 v[22:25], v[94:97], v[110:113], v[22:25]
	ds_read_b128 v[164:167], v141 offset:3072
	v_mfma_f32_16x16x32_bf16 v[26:29], v[98:101], v[110:113], v[26:29]
	ds_read_b128 v[168:171], v141 offset:5120
	v_mfma_f32_16x16x32_bf16 v[30:33], v[102:105], v[110:113], v[30:33]
	ds_read_b128 v[172:175], v141 offset:7168
	v_mfma_f32_16x16x32_bf16 v[34:37], v[90:93], v[114:117], v[34:37]
	v_mfma_f32_16x16x32_bf16 v[38:41], v[94:97], v[114:117], v[38:41]
	v_mfma_f32_16x16x32_bf16 v[42:45], v[98:101], v[114:117], v[42:45]
	v_mfma_f32_16x16x32_bf16 v[46:49], v[102:105], v[114:117], v[46:49]
	v_mfma_f32_16x16x32_bf16 v[50:53], v[90:93], v[118:121], v[50:53]
	v_mfma_f32_16x16x32_bf16 v[54:57], v[94:97], v[118:121], v[54:57]
	v_mfma_f32_16x16x32_bf16 v[58:61], v[98:101], v[118:121], v[58:61]
	v_mfma_f32_16x16x32_bf16 v[62:65], v[102:105], v[118:121], v[62:65]
	s_waitcnt vmcnt(0) lgkmcnt(0)
	s_barrier
	v_mfma_f32_16x16x32_bf16 v[2:5], v[144:147], v[160:163], v[2:5]
	ds_read_b128 v[90:93], v142 offset:32768
	s_add_u32 m0, s22, 0x0
	v_mov_b32_e32 v179, v176
	global_load_lds_dwordx4 v179, s[6:7]
	v_mfma_f32_16x16x32_bf16 v[6:9], v[148:151], v[160:163], v[6:9]
	ds_read_b128 v[94:97], v142 offset:34816
	s_add_u32 m0, s22, 0x400
	v_add_u32_e32 v180, 0x40, v176
	global_load_lds_dwordx4 v180, s[6:7]
	v_mfma_f32_16x16x32_bf16 v[10:13], v[152:155], v[160:163], v[10:13]
	ds_read_b128 v[98:101], v142 offset:36864
	s_add_u32 m0, s22, 0x800
	v_add_u32_e32 v179, 0x8000, v176
	global_load_lds_dwordx4 v179, s[6:7]
	v_mfma_f32_16x16x32_bf16 v[14:17], v[156:159], v[160:163], v[14:17]
	ds_read_b128 v[102:105], v142 offset:38912
	s_add_u32 m0, s22, 0xc00
	v_add_u32_e32 v180, 0x8040, v176
	global_load_lds_dwordx4 v180, s[6:7]
	v_mfma_f32_16x16x32_bf16 v[18:21], v[144:147], v[164:167], v[18:21]
	ds_read_b128 v[106:109], v141 offset:32768
	s_add_u32 m0, s22, 0x4000
	v_mov_b32_e32 v179, v176
	global_load_lds_dwordx4 v179, s[8:9]
	v_mfma_f32_16x16x32_bf16 v[22:25], v[148:151], v[164:167], v[22:25]
	ds_read_b128 v[110:113], v141 offset:34816
	s_add_u32 m0, s22, 0x4400
	v_add_u32_e32 v180, 0x40, v176
	global_load_lds_dwordx4 v180, s[8:9]
	v_mfma_f32_16x16x32_bf16 v[26:29], v[152:155], v[164:167], v[26:29]
	ds_read_b128 v[114:117], v141 offset:36864
	s_add_u32 m0, s22, 0x4800
	v_add_u32_e32 v179, 0x8000, v176
	global_load_lds_dwordx4 v179, s[8:9]
	v_mfma_f32_16x16x32_bf16 v[30:33], v[156:159], v[164:167], v[30:33]
	ds_read_b128 v[118:121], v141 offset:38912
	s_add_u32 m0, s22, 0x4c00
	v_add_u32_e32 v180, 0x8040, v176
	global_load_lds_dwordx4 v180, s[8:9]
	v_mfma_f32_16x16x32_bf16 v[34:37], v[144:147], v[168:171], v[34:37]
	v_mfma_f32_16x16x32_bf16 v[38:41], v[148:151], v[168:171], v[38:41]
	v_mfma_f32_16x16x32_bf16 v[42:45], v[152:155], v[168:171], v[42:45]
	v_mfma_f32_16x16x32_bf16 v[46:49], v[156:159], v[168:171], v[46:49]
	v_mfma_f32_16x16x32_bf16 v[50:53], v[144:147], v[172:175], v[50:53]
	v_mfma_f32_16x16x32_bf16 v[54:57], v[148:151], v[172:175], v[54:57]
	v_mfma_f32_16x16x32_bf16 v[58:61], v[152:155], v[172:175], v[58:61]
	v_mfma_f32_16x16x32_bf16 v[62:65], v[156:159], v[172:175], v[62:65]
	v_add_u32_e32 v176, 0x80, v176
	s_waitcnt lgkmcnt(0)
	v_mfma_f32_16x16x32_bf16 v[2:5], v[90:93], v[106:109], v[2:5]
	ds_read_b128 v[144:147], v142 offset:33792
	v_mfma_f32_16x16x32_bf16 v[6:9], v[94:97], v[106:109], v[6:9]
	ds_read_b128 v[148:151], v142 offset:35840
	v_mfma_f32_16x16x32_bf16 v[10:13], v[98:101], v[106:109], v[10:13]
	ds_read_b128 v[152:155], v142 offset:37888
	v_mfma_f32_16x16x32_bf16 v[14:17], v[102:105], v[106:109], v[14:17]
	ds_read_b128 v[156:159], v142 offset:39936
	v_mfma_f32_16x16x32_bf16 v[18:21], v[90:93], v[110:113], v[18:21]
	ds_read_b128 v[160:163], v141 offset:33792
	v_mfma_f32_16x16x32_bf16 v[22:25], v[94:97], v[110:113], v[22:25]
	ds_read_b128 v[164:167], v141 offset:35840
	v_mfma_f32_16x16x32_bf16 v[26:29], v[98:101], v[110:113], v[26:29]
	ds_read_b128 v[168:171], v141 offset:37888
	v_mfma_f32_16x16x32_bf16 v[30:33], v[102:105], v[110:113], v[30:33]
	ds_read_b128 v[172:175], v141 offset:39936
	v_mfma_f32_16x16x32_bf16 v[34:37], v[90:93], v[114:117], v[34:37]
	v_mfma_f32_16x16x32_bf16 v[38:41], v[94:97], v[114:117], v[38:41]
	v_mfma_f32_16x16x32_bf16 v[42:45], v[98:101], v[114:117], v[42:45]
	v_mfma_f32_16x16x32_bf16 v[46:49], v[102:105], v[114:117], v[46:49]
	v_mfma_f32_16x16x32_bf16 v[50:53], v[90:93], v[118:121], v[50:53]
	v_mfma_f32_16x16x32_bf16 v[54:57], v[94:97], v[118:121], v[54:57]
	v_mfma_f32_16x16x32_bf16 v[58:61], v[98:101], v[118:121], v[58:61]
	v_mfma_f32_16x16x32_bf16 v[62:65], v[102:105], v[118:121], v[62:65]
	s_waitcnt vmcnt(0) lgkmcnt(0)
	s_barrier
	v_mfma_f32_16x16x32_bf16 v[2:5], v[144:147], v[160:163], v[2:5]
	ds_read_b128 v[90:93], v142
	s_add_u32 m0, s22, 0x8000
	v_mov_b32_e32 v179, v176
	global_load_lds_dwordx4 v179, s[6:7]
	v_mfma_f32_16x16x32_bf16 v[6:9], v[148:151], v[160:163], v[6:9]
	ds_read_b128 v[94:97], v142 offset:2048
	s_add_u32 m0, s22, 0x8400
	v_add_u32_e32 v180, 0x40, v176
	global_load_lds_dwordx4 v180, s[6:7]
	v_mfma_f32_16x16x32_bf16 v[10:13], v[152:155], v[160:163], v[10:13]
	ds_read_b128 v[98:101], v142 offset:4096
	s_add_u32 m0, s22, 0x8800
	v_add_u32_e32 v179, 0x8000, v176
	global_load_lds_dwordx4 v179, s[6:7]
	v_mfma_f32_16x16x32_bf16 v[14:17], v[156:159], v[160:163], v[14:17]
	ds_read_b128 v[102:105], v142 offset:6144
	s_add_u32 m0, s22, 0x8c00
	v_add_u32_e32 v180, 0x8040, v176
	global_load_lds_dwordx4 v180, s[6:7]
	v_mfma_f32_16x16x32_bf16 v[18:21], v[144:147], v[164:167], v[18:21]
	ds_read_b128 v[106:109], v141
	s_add_u32 m0, s22, 0xc000
	v_mov_b32_e32 v179, v176
	global_load_lds_dwordx4 v179, s[8:9]
	v_mfma_f32_16x16x32_bf16 v[22:25], v[148:151], v[164:167], v[22:25]
	ds_read_b128 v[110:113], v141 offset:2048
	s_add_u32 m0, s22, 0xc400
	v_add_u32_e32 v180, 0x40, v176
	global_load_lds_dwordx4 v180, s[8:9]
	v_mfma_f32_16x16x32_bf16 v[26:29], v[152:155], v[164:167], v[26:29]
	ds_read_b128 v[114:117], v141 offset:4096
	s_add_u32 m0, s22, 0xc800
	v_add_u32_e32 v179, 0x8000, v176
	global_load_lds_dwordx4 v179, s[8:9]
	v_mfma_f32_16x16x32_bf16 v[30:33], v[156:159], v[164:167], v[30:33]
	ds_read_b128 v[118:121], v141 offset:6144
	s_add_u32 m0, s22, 0xcc00
	v_add_u32_e32 v180, 0x8040, v176
	global_load_lds_dwordx4 v180, s[8:9]
	v_mfma_f32_16x16x32_bf16 v[34:37], v[144:147], v[168:171], v[34:37]
	v_mfma_f32_16x16x32_bf16 v[38:41], v[148:151], v[168:171], v[38:41]
	v_mfma_f32_16x16x32_bf16 v[42:45], v[152:155], v[168:171], v[42:45]
	v_mfma_f32_16x16x32_bf16 v[46:49], v[156:159], v[168:171], v[46:49]
	v_mfma_f32_16x16x32_bf16 v[50:53], v[144:147], v[172:175], v[50:53]
	v_mfma_f32_16x16x32_bf16 v[54:57], v[148:151], v[172:175], v[54:57]
	v_mfma_f32_16x16x32_bf16 v[58:61], v[152:155], v[172:175], v[58:61]
	v_mfma_f32_16x16x32_bf16 v[62:65], v[156:159], v[172:175], v[62:65]
	v_add_u32_e32 v176, 0x80, v176
	s_sub_u32 s16, s16, 1
	s_cmp_lg_u32 s16, 0
	s_cbranch_scc1 .Lg128_w1_loop
	s_add_u32 s12, s12, s83
.Lg128_w1_next_retry:
	s_cmp_ge_u32 s12, 512
	s_cbranch_scc1 .Lg128_w1_nonext
	s_lshr_b32 s3, s12, 6
	s_lshl_b32 s3, s3, 3
	s_add_u32 s3, s3, s65
	s_lshr_b32 s17, s3, 2
	s_and_b32 s3, s3, 3
	s_lshl_b32 s17, s17, 3
	s_bfe_u32 s23, s12, 0x30003
	s_add_u32 s13, s17, s23
	s_lshl_b32 s3, s3, 3
	s_and_b32 s23, s12, 7
	s_add_u32 s14, s3, s23
	s_lshl_b32 s13, s13, 7
	s_lshl_b32 s14, s14, 7
	s_lshl_b32 s3, s15, 5
	s_add_u32 s17, s3, s13
	s_mul_i32 s17, s17, 0x800
	s_add_u32 s6, s18, s17
	s_addc_u32 s7, s19, 0
	s_add_u32 s17, s3, s14
	s_mul_i32 s17, s17, 0x800
	s_add_u32 s8, s20, s17
	s_addc_u32 s9, s21, 0
	v_mov_b32_e32 v176, v177
	s_mov_b32 s16, 1
	s_waitcnt lgkmcnt(0)
	v_mfma_f32_16x16x32_bf16 v[2:5], v[90:93], v[106:109], v[2:5]
	ds_read_b128 v[144:147], v142 offset:1024
	v_mfma_f32_16x16x32_bf16 v[6:9], v[94:97], v[106:109], v[6:9]
	ds_read_b128 v[148:151], v142 offset:3072
	v_mfma_f32_16x16x32_bf16 v[10:13], v[98:101], v[106:109], v[10:13]
	ds_read_b128 v[152:155], v142 offset:5120
	v_mfma_f32_16x16x32_bf16 v[14:17], v[102:105], v[106:109], v[14:17]
	ds_read_b128 v[156:159], v142 offset:7168
	v_mfma_f32_16x16x32_bf16 v[18:21], v[90:93], v[110:113], v[18:21]
	ds_read_b128 v[160:163], v141 offset:1024
	v_mfma_f32_16x16x32_bf16 v[22:25], v[94:97], v[110:113], v[22:25]
	ds_read_b128 v[164:167], v141 offset:3072
	v_mfma_f32_16x16x32_bf16 v[26:29], v[98:101], v[110:113], v[26:29]
	ds_read_b128 v[168:171], v141 offset:5120
	v_mfma_f32_16x16x32_bf16 v[30:33], v[102:105], v[110:113], v[30:33]
	ds_read_b128 v[172:175], v141 offset:7168
	v_mfma_f32_16x16x32_bf16 v[34:37], v[90:93], v[114:117], v[34:37]
	v_mfma_f32_16x16x32_bf16 v[38:41], v[94:97], v[114:117], v[38:41]
	v_mfma_f32_16x16x32_bf16 v[42:45], v[98:101], v[114:117], v[42:45]
	v_mfma_f32_16x16x32_bf16 v[46:49], v[102:105], v[114:117], v[46:49]
	v_mfma_f32_16x16x32_bf16 v[50:53], v[90:93], v[118:121], v[50:53]
	v_mfma_f32_16x16x32_bf16 v[54:57], v[94:97], v[118:121], v[54:57]
	v_mfma_f32_16x16x32_bf16 v[58:61], v[98:101], v[118:121], v[58:61]
	v_mfma_f32_16x16x32_bf16 v[62:65], v[102:105], v[118:121], v[62:65]
	s_waitcnt vmcnt(0) lgkmcnt(0)
	s_barrier
	v_mfma_f32_16x16x32_bf16 v[2:5], v[144:147], v[160:163], v[2:5]
	ds_read_b128 v[90:93], v142 offset:32768
	s_add_u32 m0, s22, 0x0
	v_mov_b32_e32 v179, v176
	global_load_lds_dwordx4 v179, s[6:7]
	v_mfma_f32_16x16x32_bf16 v[6:9], v[148:151], v[160:163], v[6:9]
	ds_read_b128 v[94:97], v142 offset:34816
	s_add_u32 m0, s22, 0x400
	v_add_u32_e32 v180, 0x40, v176
	global_load_lds_dwordx4 v180, s[6:7]
	v_mfma_f32_16x16x32_bf16 v[10:13], v[152:155], v[160:163], v[10:13]
	ds_read_b128 v[98:101], v142 offset:36864
	s_add_u32 m0, s22, 0x800
	v_add_u32_e32 v179, 0x8000, v176
	global_load_lds_dwordx4 v179, s[6:7]
	v_mfma_f32_16x16x32_bf16 v[14:17], v[156:159], v[160:163], v[14:17]
	ds_read_b128 v[102:105], v142 offset:38912
	s_add_u32 m0, s22, 0xc00
	v_add_u32_e32 v180, 0x8040, v176
	global_load_lds_dwordx4 v180, s[6:7]
	v_mfma_f32_16x16x32_bf16 v[18:21], v[144:147], v[164:167], v[18:21]
	ds_read_b128 v[106:109], v141 offset:32768
	s_add_u32 m0, s22, 0x4000
	v_mov_b32_e32 v179, v176
	global_load_lds_dwordx4 v179, s[8:9]
	v_mfma_f32_16x16x32_bf16 v[22:25], v[148:151], v[164:167], v[22:25]
	ds_read_b128 v[110:113], v141 offset:34816
	s_add_u32 m0, s22, 0x4400
	v_add_u32_e32 v180, 0x40, v176
	global_load_lds_dwordx4 v180, s[8:9]
	v_mfma_f32_16x16x32_bf16 v[26:29], v[152:155], v[164:167], v[26:29]
	ds_read_b128 v[114:117], v141 offset:36864
	s_add_u32 m0, s22, 0x4800
	v_add_u32_e32 v179, 0x8000, v176
	global_load_lds_dwordx4 v179, s[8:9]
	v_mfma_f32_16x16x32_bf16 v[30:33], v[156:159], v[164:167], v[30:33]
	ds_read_b128 v[118:121], v141 offset:38912
	s_add_u32 m0, s22, 0x4c00
	v_add_u32_e32 v180, 0x8040, v176
	global_load_lds_dwordx4 v180, s[8:9]
	v_mfma_f32_16x16x32_bf16 v[34:37], v[144:147], v[168:171], v[34:37]
	v_mfma_f32_16x16x32_bf16 v[38:41], v[148:151], v[168:171], v[38:41]
	v_mfma_f32_16x16x32_bf16 v[42:45], v[152:155], v[168:171], v[42:45]
	v_mfma_f32_16x16x32_bf16 v[46:49], v[156:159], v[168:171], v[46:49]
	v_mfma_f32_16x16x32_bf16 v[50:53], v[144:147], v[172:175], v[50:53]
	v_mfma_f32_16x16x32_bf16 v[54:57], v[148:151], v[172:175], v[54:57]
	v_mfma_f32_16x16x32_bf16 v[58:61], v[152:155], v[172:175], v[58:61]
	v_mfma_f32_16x16x32_bf16 v[62:65], v[156:159], v[172:175], v[62:65]
	v_add_u32_e32 v176, 0x80, v176
	s_waitcnt lgkmcnt(0)
	v_mfma_f32_16x16x32_bf16 v[2:5], v[90:93], v[106:109], v[2:5]
	ds_read_b128 v[144:147], v142 offset:33792
	v_mfma_f32_16x16x32_bf16 v[6:9], v[94:97], v[106:109], v[6:9]
	ds_read_b128 v[148:151], v142 offset:35840
	v_mfma_f32_16x16x32_bf16 v[10:13], v[98:101], v[106:109], v[10:13]
	ds_read_b128 v[152:155], v142 offset:37888
	v_mfma_f32_16x16x32_bf16 v[14:17], v[102:105], v[106:109], v[14:17]
	ds_read_b128 v[156:159], v142 offset:39936
	v_mfma_f32_16x16x32_bf16 v[18:21], v[90:93], v[110:113], v[18:21]
	ds_read_b128 v[160:163], v141 offset:33792
	v_mfma_f32_16x16x32_bf16 v[22:25], v[94:97], v[110:113], v[22:25]
	ds_read_b128 v[164:167], v141 offset:35840
	v_mfma_f32_16x16x32_bf16 v[26:29], v[98:101], v[110:113], v[26:29]
	ds_read_b128 v[168:171], v141 offset:37888
	v_mfma_f32_16x16x32_bf16 v[30:33], v[102:105], v[110:113], v[30:33]
	ds_read_b128 v[172:175], v141 offset:39936
	v_mfma_f32_16x16x32_bf16 v[34:37], v[90:93], v[114:117], v[34:37]
	v_mfma_f32_16x16x32_bf16 v[38:41], v[94:97], v[114:117], v[38:41]
	v_mfma_f32_16x16x32_bf16 v[42:45], v[98:101], v[114:117], v[42:45]
	v_mfma_f32_16x16x32_bf16 v[46:49], v[102:105], v[114:117], v[46:49]
	v_mfma_f32_16x16x32_bf16 v[50:53], v[90:93], v[118:121], v[50:53]
	v_mfma_f32_16x16x32_bf16 v[54:57], v[94:97], v[118:121], v[54:57]
	v_mfma_f32_16x16x32_bf16 v[58:61], v[98:101], v[118:121], v[58:61]
	v_mfma_f32_16x16x32_bf16 v[62:65], v[102:105], v[118:121], v[62:65]
	s_waitcnt vmcnt(0) lgkmcnt(0)
	s_barrier
	v_mfma_f32_16x16x32_bf16 v[2:5], v[144:147], v[160:163], v[2:5]
	ds_read_b128 v[90:93], v142
	s_add_u32 m0, s22, 0x8000
	v_mov_b32_e32 v179, v176
	global_load_lds_dwordx4 v179, s[6:7]
	v_mfma_f32_16x16x32_bf16 v[6:9], v[148:151], v[160:163], v[6:9]
	ds_read_b128 v[94:97], v142 offset:2048
	s_add_u32 m0, s22, 0x8400
	v_add_u32_e32 v180, 0x40, v176
	global_load_lds_dwordx4 v180, s[6:7]
	v_mfma_f32_16x16x32_bf16 v[10:13], v[152:155], v[160:163], v[10:13]
	ds_read_b128 v[98:101], v142 offset:4096
	s_add_u32 m0, s22, 0x8800
	v_add_u32_e32 v179, 0x8000, v176
	global_load_lds_dwordx4 v179, s[6:7]
	v_mfma_f32_16x16x32_bf16 v[14:17], v[156:159], v[160:163], v[14:17]
	ds_read_b128 v[102:105], v142 offset:6144
	s_add_u32 m0, s22, 0x8c00
	v_add_u32_e32 v180, 0x8040, v176
	global_load_lds_dwordx4 v180, s[6:7]
	v_mfma_f32_16x16x32_bf16 v[18:21], v[144:147], v[164:167], v[18:21]
	ds_read_b128 v[106:109], v141
	s_add_u32 m0, s22, 0xc000
	v_mov_b32_e32 v179, v176
	global_load_lds_dwordx4 v179, s[8:9]
	v_mfma_f32_16x16x32_bf16 v[22:25], v[148:151], v[164:167], v[22:25]
	ds_read_b128 v[110:113], v141 offset:2048
	s_add_u32 m0, s22, 0xc400
	v_add_u32_e32 v180, 0x40, v176
	global_load_lds_dwordx4 v180, s[8:9]
	v_mfma_f32_16x16x32_bf16 v[26:29], v[152:155], v[164:167], v[26:29]
	ds_read_b128 v[114:117], v141 offset:4096
	s_add_u32 m0, s22, 0xc800
	v_add_u32_e32 v179, 0x8000, v176
	global_load_lds_dwordx4 v179, s[8:9]
	v_mfma_f32_16x16x32_bf16 v[30:33], v[156:159], v[164:167], v[30:33]
	ds_read_b128 v[118:121], v141 offset:6144
	s_add_u32 m0, s22, 0xcc00
	v_add_u32_e32 v180, 0x8040, v176
	global_load_lds_dwordx4 v180, s[8:9]
	v_mfma_f32_16x16x32_bf16 v[34:37], v[144:147], v[168:171], v[34:37]
	v_mfma_f32_16x16x32_bf16 v[38:41], v[148:151], v[168:171], v[38:41]
	v_mfma_f32_16x16x32_bf16 v[42:45], v[152:155], v[168:171], v[42:45]
	v_mfma_f32_16x16x32_bf16 v[46:49], v[156:159], v[168:171], v[46:49]
	v_mfma_f32_16x16x32_bf16 v[50:53], v[144:147], v[172:175], v[50:53]
	v_mfma_f32_16x16x32_bf16 v[54:57], v[148:151], v[172:175], v[54:57]
	v_mfma_f32_16x16x32_bf16 v[58:61], v[152:155], v[172:175], v[58:61]
	v_mfma_f32_16x16x32_bf16 v[62:65], v[156:159], v[172:175], v[62:65]
	v_add_u32_e32 v176, 0x80, v176
	s_branch .Lg128_w1_epi

.Lg128_w1_epi:
	v_max_f32_e32 v2, 0, v2
	v_max_f32_e32 v3, 0, v3
	v_max_f32_e32 v4, 0, v4
	v_max_f32_e32 v5, 0, v5
	v_pk_mul_f32 v[2:3], v[2:3], v[2:3]
	v_pk_mul_f32 v[4:5], v[4:5], v[4:5]
	v_cvt_pk_bf16_f32 v2, v2, v3
	v_cvt_pk_bf16_f32 v3, v4, v5
	global_store_dwordx2 v178, v[2:3], s[10:11]
	v_max_f32_e32 v6, 0, v6
	v_max_f32_e32 v7, 0, v7
	v_max_f32_e32 v8, 0, v8
	v_max_f32_e32 v9, 0, v9
	v_pk_mul_f32 v[6:7], v[6:7], v[6:7]
	v_pk_mul_f32 v[8:9], v[8:9], v[8:9]
	v_cvt_pk_bf16_f32 v6, v6, v7
	v_cvt_pk_bf16_f32 v7, v8, v9
	global_store_dwordx2 v178, v[6:7], s[10:11] offset:32
	v_max_f32_e32 v10, 0, v10
	v_max_f32_e32 v11, 0, v11
	v_max_f32_e32 v12, 0, v12
	v_max_f32_e32 v13, 0, v13
	v_pk_mul_f32 v[10:11], v[10:11], v[10:11]
	v_pk_mul_f32 v[12:13], v[12:13], v[12:13]
	v_cvt_pk_bf16_f32 v10, v10, v11
	v_cvt_pk_bf16_f32 v11, v12, v13
	global_store_dwordx2 v178, v[10:11], s[10:11] offset:64
	v_max_f32_e32 v14, 0, v14
	v_max_f32_e32 v15, 0, v15
	v_max_f32_e32 v16, 0, v16
	v_max_f32_e32 v17, 0, v17
	v_pk_mul_f32 v[14:15], v[14:15], v[14:15]
	v_pk_mul_f32 v[16:17], v[16:17], v[16:17]
	v_cvt_pk_bf16_f32 v14, v14, v15
	v_cvt_pk_bf16_f32 v15, v16, v17
	global_store_dwordx2 v178, v[14:15], s[10:11] offset:96
	v_add_u32_e32 v131, 0x20000, v178
	v_max_f32_e32 v18, 0, v18
	v_max_f32_e32 v19, 0, v19
	v_max_f32_e32 v20, 0, v20
	v_max_f32_e32 v21, 0, v21
	v_pk_mul_f32 v[18:19], v[18:19], v[18:19]
	v_pk_mul_f32 v[20:21], v[20:21], v[20:21]
	v_cvt_pk_bf16_f32 v18, v18, v19
	v_cvt_pk_bf16_f32 v19, v20, v21
	global_store_dwordx2 v131, v[18:19], s[10:11]
	v_max_f32_e32 v22, 0, v22
	v_max_f32_e32 v23, 0, v23
	v_max_f32_e32 v24, 0, v24
	v_max_f32_e32 v25, 0, v25
	v_pk_mul_f32 v[22:23], v[22:23], v[22:23]
	v_pk_mul_f32 v[24:25], v[24:25], v[24:25]
	v_cvt_pk_bf16_f32 v22, v22, v23
	v_cvt_pk_bf16_f32 v23, v24, v25
	global_store_dwordx2 v131, v[22:23], s[10:11] offset:32
	v_max_f32_e32 v26, 0, v26
	v_max_f32_e32 v27, 0, v27
	v_max_f32_e32 v28, 0, v28
	v_max_f32_e32 v29, 0, v29
	v_pk_mul_f32 v[26:27], v[26:27], v[26:27]
	v_pk_mul_f32 v[28:29], v[28:29], v[28:29]
	v_cvt_pk_bf16_f32 v26, v26, v27
	v_cvt_pk_bf16_f32 v27, v28, v29
	global_store_dwordx2 v131, v[26:27], s[10:11] offset:64
	v_max_f32_e32 v30, 0, v30
	v_max_f32_e32 v31, 0, v31
	v_max_f32_e32 v32, 0, v32
	v_max_f32_e32 v33, 0, v33
	v_pk_mul_f32 v[30:31], v[30:31], v[30:31]
	v_pk_mul_f32 v[32:33], v[32:33], v[32:33]
	v_cvt_pk_bf16_f32 v30, v30, v31
	v_cvt_pk_bf16_f32 v31, v32, v33
	global_store_dwordx2 v131, v[30:31], s[10:11] offset:96
	v_add_u32_e32 v131, 0x40000, v178
	v_max_f32_e32 v34, 0, v34
	v_max_f32_e32 v35, 0, v35
	v_max_f32_e32 v36, 0, v36
	v_max_f32_e32 v37, 0, v37
	v_pk_mul_f32 v[34:35], v[34:35], v[34:35]
	v_pk_mul_f32 v[36:37], v[36:37], v[36:37]
	v_cvt_pk_bf16_f32 v34, v34, v35
	v_cvt_pk_bf16_f32 v35, v36, v37
	global_store_dwordx2 v131, v[34:35], s[10:11]
	v_max_f32_e32 v38, 0, v38
	v_max_f32_e32 v39, 0, v39
	v_max_f32_e32 v40, 0, v40
	v_max_f32_e32 v41, 0, v41
	v_pk_mul_f32 v[38:39], v[38:39], v[38:39]
	v_pk_mul_f32 v[40:41], v[40:41], v[40:41]
	v_cvt_pk_bf16_f32 v38, v38, v39
	v_cvt_pk_bf16_f32 v39, v40, v41
	global_store_dwordx2 v131, v[38:39], s[10:11] offset:32
	v_max_f32_e32 v42, 0, v42
	v_max_f32_e32 v43, 0, v43
	v_max_f32_e32 v44, 0, v44
	v_max_f32_e32 v45, 0, v45
	v_pk_mul_f32 v[42:43], v[42:43], v[42:43]
	v_pk_mul_f32 v[44:45], v[44:45], v[44:45]
	v_cvt_pk_bf16_f32 v42, v42, v43
	v_cvt_pk_bf16_f32 v43, v44, v45
	global_store_dwordx2 v131, v[42:43], s[10:11] offset:64
	v_max_f32_e32 v46, 0, v46
	v_max_f32_e32 v47, 0, v47
	v_max_f32_e32 v48, 0, v48
	v_max_f32_e32 v49, 0, v49
	v_pk_mul_f32 v[46:47], v[46:47], v[46:47]
	v_pk_mul_f32 v[48:49], v[48:49], v[48:49]
	v_cvt_pk_bf16_f32 v46, v46, v47
	v_cvt_pk_bf16_f32 v47, v48, v49
	global_store_dwordx2 v131, v[46:47], s[10:11] offset:96
	v_add_u32_e32 v131, 0x60000, v178
	v_max_f32_e32 v50, 0, v50
	v_max_f32_e32 v51, 0, v51
	v_max_f32_e32 v52, 0, v52
	v_max_f32_e32 v53, 0, v53
	v_pk_mul_f32 v[50:51], v[50:51], v[50:51]
	v_pk_mul_f32 v[52:53], v[52:53], v[52:53]
	v_cvt_pk_bf16_f32 v50, v50, v51
	v_cvt_pk_bf16_f32 v51, v52, v53
	global_store_dwordx2 v131, v[50:51], s[10:11]
	v_max_f32_e32 v54, 0, v54
	v_max_f32_e32 v55, 0, v55
	v_max_f32_e32 v56, 0, v56
	v_max_f32_e32 v57, 0, v57
	v_pk_mul_f32 v[54:55], v[54:55], v[54:55]
	v_pk_mul_f32 v[56:57], v[56:57], v[56:57]
	v_cvt_pk_bf16_f32 v54, v54, v55
	v_cvt_pk_bf16_f32 v55, v56, v57
	global_store_dwordx2 v131, v[54:55], s[10:11] offset:32
	v_max_f32_e32 v58, 0, v58
	v_max_f32_e32 v59, 0, v59
	v_max_f32_e32 v60, 0, v60
	v_max_f32_e32 v61, 0, v61
	v_pk_mul_f32 v[58:59], v[58:59], v[58:59]
	v_pk_mul_f32 v[60:61], v[60:61], v[60:61]
	v_cvt_pk_bf16_f32 v58, v58, v59
	v_cvt_pk_bf16_f32 v59, v60, v61
	global_store_dwordx2 v131, v[58:59], s[10:11] offset:64
	v_max_f32_e32 v62, 0, v62
	v_max_f32_e32 v63, 0, v63
	v_max_f32_e32 v64, 0, v64
	v_max_f32_e32 v65, 0, v65
	v_pk_mul_f32 v[62:63], v[62:63], v[62:63]
	v_pk_mul_f32 v[64:65], v[64:65], v[64:65]
	v_cvt_pk_bf16_f32 v62, v62, v63
	v_cvt_pk_bf16_f32 v63, v64, v65
	global_store_dwordx2 v131, v[62:63], s[10:11] offset:96
	s_cmp_lg_u32 s16, 0
	s_cbranch_scc1 .Lg128_w1_tile

.LBB0_60:
	s_andn2_b64 vcc, exec, s[4:5]
	s_cbranch_vccnz .LBB0_66
	v_readlane_b32 s4, v239, 0
	v_readlane_b32 s5, v239, 1
	s_andn2_b64 vcc, exec, s[4:5]
	s_cbranch_vccnz .LBB0_66
	s_load_dwordx2 s[4:5], s[0:1], 0x130
	s_load_dwordx2 s[24:25], s[0:1], 0x128
	v_and_b32_e32 v0, 63, v133
	v_lshrrev_b32_e32 v131, 6, v133
	v_lshrrev_b32_e32 v195, 2, v0
	v_readfirstlane_b32 s15, v131
	v_mul_u32_u24_e32 v177, 0x800, v195
	v_and_b32_e32 v195, 3, v0
	v_lshlrev_b32_e32 v195, 4, v195
	v_lshrrev_b32_e32 v131, 5, v0
	v_lshlrev_b32_e32 v131, 5, v131
	v_xor_b32_e32 v195, v195, v131
	v_add_u32_e32 v177, v177, v195
	v_and_b32_e32 v195, 15, v0
	v_lshrrev_b32_e32 v131, 4, v0
	v_lshlrev_b32_e32 v141, 6, v195
	v_lshl_or_b32 v141, v131, 4, v141
	v_and_b32_e32 v178, 8, v0
	v_lshlrev_b32_e32 v178, 2, v178
	v_xor_b32_e32 v141, v141, v178
	v_mul_u32_u24_e32 v178, 0x1000, v195
	v_lshl_or_b32 v178, v131, 4, v178
	s_waitcnt lgkmcnt(0)
	s_add_u32 s18, s4, 0x4b27800
	s_addc_u32 s19, s5, 0
	s_add_u32 s20, s4, 0x1927800
	s_addc_u32 s21, s5, 0
	s_mul_i32 s3, s62, 73728
	s_add_u32 s3, s3, 8192
	s_add_u32 s4, s4, s3
	s_addc_u32 s5, s5, 0
	v_lshlrev_b32_e32 v143, 4, v131
	s_and_b32 s3, s15, 1
	s_lshl_b32 s3, s3, 13
	s_add_u32 s3, s3, 16384
	v_add_u32_e32 v142, s3, v141
	s_lshr_b32 s3, s15, 1
	s_lshl_b32 s3, s3, 13
	v_add_u32_e32 v141, s3, v141
	s_lshl_b32 s22, s15, 12
	s_mov_b32 s12, s79
.Lg128_wo_first_retry:
	s_cmp_ge_u32 s12, 128
	s_cbranch_scc1 .Lg128_wo_done
	s_lshr_b32 s3, s12, 6
	s_lshl_b32 s3, s3, 3
	s_add_u32 s3, s3, s65
	s_mov_b32 s17, s3
	s_mov_b32 s3, 0
	s_lshl_b32 s17, s17, 3
	s_bfe_u32 s23, s12, 0x30003
	s_add_u32 s13, s17, s23
	s_lshl_b32 s3, s3, 3
	s_and_b32 s23, s12, 7
	s_add_u32 s14, s3, s23
	s_lshl_b32 s13, s13, 7
	s_lshl_b32 s14, s14, 7
	s_lshl_b32 s3, s15, 5
	s_add_u32 s17, s3, s13
	s_mul_i32 s17, s17, 0x800
	s_add_u32 s6, s18, s17
	s_addc_u32 s7, s19, 0
	s_add_u32 s17, s3, s14
	s_mul_i32 s17, s17, 0x800
	s_add_u32 s8, s20, s17
	s_addc_u32 s9, s21, 0
	s_barrier
	v_mov_b32_e32 v176, v177
	s_add_u32 m0, s22, 0x0
	v_mov_b32_e32 v179, v176
	global_load_lds_dwordx4 v179, s[6:7]
	s_add_u32 m0, s22, 0x400
	v_add_u32_e32 v180, 0x40, v176
	global_load_lds_dwordx4 v180, s[6:7]
	s_add_u32 m0, s22, 0x800
	v_add_u32_e32 v179, 0x8000, v176
	global_load_lds_dwordx4 v179, s[6:7]
	s_add_u32 m0, s22, 0xc00
	v_add_u32_e32 v180, 0x8040, v176
	global_load_lds_dwordx4 v180, s[6:7]
	s_add_u32 m0, s22, 0x4000
	v_mov_b32_e32 v179, v176
	global_load_lds_dwordx4 v179, s[8:9]
	s_add_u32 m0, s22, 0x4400
	v_add_u32_e32 v180, 0x40, v176
	global_load_lds_dwordx4 v180, s[8:9]
	s_add_u32 m0, s22, 0x4800
	v_add_u32_e32 v179, 0x8000, v176
	global_load_lds_dwordx4 v179, s[8:9]
	s_add_u32 m0, s22, 0x4c00
	v_add_u32_e32 v180, 0x8040, v176
	global_load_lds_dwordx4 v180, s[8:9]
	v_add_u32_e32 v176, 0x80, v176
	s_add_u32 m0, s22, 0x8000
	v_mov_b32_e32 v179, v176
	global_load_lds_dwordx4 v179, s[6:7]
	s_add_u32 m0, s22, 0x8400
	v_add_u32_e32 v180, 0x40, v176
	global_load_lds_dwordx4 v180, s[6:7]
	s_add_u32 m0, s22, 0x8800
	v_add_u32_e32 v179, 0x8000, v176
	global_load_lds_dwordx4 v179, s[6:7]
	s_add_u32 m0, s22, 0x8c00
	v_add_u32_e32 v180, 0x8040, v176
	global_load_lds_dwordx4 v180, s[6:7]
	s_add_u32 m0, s22, 0xc000
	v_mov_b32_e32 v179, v176
	global_load_lds_dwordx4 v179, s[8:9]
	s_add_u32 m0, s22, 0xc400
	v_add_u32_e32 v180, 0x40, v176
	global_load_lds_dwordx4 v180, s[8:9]
	s_add_u32 m0, s22, 0xc800
	v_add_u32_e32 v179, 0x8000, v176
	global_load_lds_dwordx4 v179, s[8:9]
	s_add_u32 m0, s22, 0xcc00
	v_add_u32_e32 v180, 0x8040, v176
	global_load_lds_dwordx4 v180, s[8:9]
	v_add_u32_e32 v176, 0x80, v176
	s_waitcnt vmcnt(0)
	s_barrier
	ds_read_b128 v[90:93], v142
	ds_read_b128 v[94:97], v142 offset:2048
	ds_read_b128 v[98:101], v142 offset:4096
	ds_read_b128 v[102:105], v142 offset:6144
	ds_read_b128 v[106:109], v141
	ds_read_b128 v[110:113], v141 offset:2048
	ds_read_b128 v[114:117], v141 offset:4096
	ds_read_b128 v[118:121], v141 offset:6144
.Lg128_wo_tile:
	s_lshr_b32 s3, s15, 1
	s_lshl_b32 s3, s3, 6
	s_add_u32 s3, s3, s13
	s_mul_i32 s17, s3, 0x1000
	s_and_b32 s3, s15, 1
	s_lshl_b32 s3, s3, 6
	s_add_u32 s3, s3, s14
	s_mul_i32 s3, s3, 4
	s_add_u32 s17, s17, s3
	s_add_u32 s10, s24, s17
	s_addc_u32 s11, s25, 0
	s_lshr_b32 s17, s13, 12
	s_max_u32 s17, s17, 1
	s_sub_u32 s17, s17, 1
	s_mul_i32 s17, s17, 24576
	s_add_u32 s3, s3, s17
	v_add_u32_e32 v181, s3, v143
	s_cmp_lg_u32 s62, 0
	s_cbranch_scc1 .Lg128_wo_x_l1_0
	s_lshr_b32 s3, s13, 13
	s_lshl_b32 s3, s3, 3
	s_load_dwordx2 s[26:27], s[0:1], s3
	s_lshl_b32 s17, s13, 12
	s_and_b32 s17, s17, 0x1ffffff
	s_lshr_b32 s3, s15, 1
	s_lshl_b32 s3, s3, 18
	s_add_u32 s17, s17, s3
	s_and_b32 s3, s15, 1
	s_lshl_b32 s3, s3, 6
	s_add_u32 s3, s3, s14
	s_lshl_b32 s3, s3, 2
	s_add_u32 s17, s17, s3
	s_waitcnt lgkmcnt(0)
	s_add_u32 s26, s26, s17
	s_addc_u32 s27, s27, 0
	s_branch .Lg128_wo_x_go_0
.Lg128_wo_x_l1_0:
	s_mov_b64 s[26:27], s[10:11]
.Lg128_wo_x_go_0:
	s_waitcnt lgkmcnt(0)
	v_mfma_f32_16x16x32_bf16 v[2:5], v[90:93], v[106:109], 0
	ds_read_b128 v[144:147], v142 offset:1024
	v_mfma_f32_16x16x32_bf16 v[6:9], v[94:97], v[106:109], 0
	ds_read_b128 v[148:151], v142 offset:3072
	v_mfma_f32_16x16x32_bf16 v[10:13], v[98:101], v[106:109], 0
	ds_read_b128 v[152:155], v142 offset:5120
	v_mfma_f32_16x16x32_bf16 v[14:17], v[102:105], v[106:109], 0
	ds_read_b128 v[156:159], v142 offset:7168
	v_mfma_f32_16x16x32_bf16 v[18:21], v[90:93], v[110:113], 0
	ds_read_b128 v[160:163], v141 offset:1024
	v_mfma_f32_16x16x32_bf16 v[22:25], v[94:97], v[110:113], 0
	ds_read_b128 v[164:167], v141 offset:3072
	v_mfma_f32_16x16x32_bf16 v[26:29], v[98:101], v[110:113], 0
	ds_read_b128 v[168:171], v141 offset:5120
	v_mfma_f32_16x16x32_bf16 v[30:33], v[102:105], v[110:113], 0
	ds_read_b128 v[172:175], v141 offset:7168
	v_mfma_f32_16x16x32_bf16 v[34:37], v[90:93], v[114:117], 0
	v_mfma_f32_16x16x32_bf16 v[38:41], v[94:97], v[114:117], 0
	v_mfma_f32_16x16x32_bf16 v[42:45], v[98:101], v[114:117], 0
	v_mfma_f32_16x16x32_bf16 v[46:49], v[102:105], v[114:117], 0
	v_mfma_f32_16x16x32_bf16 v[50:53], v[90:93], v[118:121], 0
	v_mfma_f32_16x16x32_bf16 v[54:57], v[94:97], v[118:121], 0
	v_mfma_f32_16x16x32_bf16 v[58:61], v[98:101], v[118:121], 0
	v_mfma_f32_16x16x32_bf16 v[62:65], v[102:105], v[118:121], 0
	s_waitcnt vmcnt(16) lgkmcnt(0)
	s_barrier
	v_mfma_f32_16x16x32_bf16 v[2:5], v[144:147], v[160:163], v[2:5]
	ds_read_b128 v[90:93], v142 offset:32768
	s_add_u32 m0, s22, 0x0
	v_mov_b32_e32 v179, v176
	global_load_lds_dwordx4 v179, s[6:7]
	v_mfma_f32_16x16x32_bf16 v[6:9], v[148:151], v[160:163], v[6:9]
	ds_read_b128 v[94:97], v142 offset:34816
	s_add_u32 m0, s22, 0x400
	v_add_u32_e32 v180, 0x40, v176
	global_load_lds_dwordx4 v180, s[6:7]
	v_mfma_f32_16x16x32_bf16 v[10:13], v[152:155], v[160:163], v[10:13]
	ds_read_b128 v[98:101], v142 offset:36864
	s_add_u32 m0, s22, 0x800
	v_add_u32_e32 v179, 0x8000, v176
	global_load_lds_dwordx4 v179, s[6:7]
	v_mfma_f32_16x16x32_bf16 v[14:17], v[156:159], v[160:163], v[14:17]
	ds_read_b128 v[102:105], v142 offset:38912
	s_add_u32 m0, s22, 0xc00
	v_add_u32_e32 v180, 0x8040, v176
	global_load_lds_dwordx4 v180, s[6:7]
	v_mfma_f32_16x16x32_bf16 v[18:21], v[144:147], v[164:167], v[18:21]
	ds_read_b128 v[106:109], v141 offset:32768
	s_add_u32 m0, s22, 0x4000
	v_mov_b32_e32 v179, v176
	global_load_lds_dwordx4 v179, s[8:9]
	v_mfma_f32_16x16x32_bf16 v[22:25], v[148:151], v[164:167], v[22:25]
	ds_read_b128 v[110:113], v141 offset:34816
	s_add_u32 m0, s22, 0x4400
	v_add_u32_e32 v180, 0x40, v176
	global_load_lds_dwordx4 v180, s[8:9]
	v_mfma_f32_16x16x32_bf16 v[26:29], v[152:155], v[164:167], v[26:29]
	ds_read_b128 v[114:117], v141 offset:36864
	s_add_u32 m0, s22, 0x4800
	v_add_u32_e32 v179, 0x8000, v176
	global_load_lds_dwordx4 v179, s[8:9]
	v_mfma_f32_16x16x32_bf16 v[30:33], v[156:159], v[164:167], v[30:33]
	ds_read_b128 v[118:121], v141 offset:38912
	s_add_u32 m0, s22, 0x4c00
	v_add_u32_e32 v180, 0x8040, v176
	global_load_lds_dwordx4 v180, s[8:9]
	v_mfma_f32_16x16x32_bf16 v[34:37], v[144:147], v[168:171], v[34:37]
	v_mfma_f32_16x16x32_bf16 v[38:41], v[148:151], v[168:171], v[38:41]
	v_mfma_f32_16x16x32_bf16 v[42:45], v[152:155], v[168:171], v[42:45]
	v_mfma_f32_16x16x32_bf16 v[46:49], v[156:159], v[168:171], v[46:49]
	v_mfma_f32_16x16x32_bf16 v[50:53], v[144:147], v[172:175], v[50:53]
	v_mfma_f32_16x16x32_bf16 v[54:57], v[148:151], v[172:175], v[54:57]
	v_mfma_f32_16x16x32_bf16 v[58:61], v[152:155], v[172:175], v[58:61]
	v_mfma_f32_16x16x32_bf16 v[62:65], v[156:159], v[172:175], v[62:65]
	v_add_u32_e32 v176, 0x80, v176
	s_waitcnt lgkmcnt(0)
	v_mfma_f32_16x16x32_bf16 v[2:5], v[90:93], v[106:109], v[2:5]
	ds_read_b128 v[144:147], v142 offset:33792
	v_mfma_f32_16x16x32_bf16 v[6:9], v[94:97], v[106:109], v[6:9]
	ds_read_b128 v[148:151], v142 offset:35840
	v_mfma_f32_16x16x32_bf16 v[10:13], v[98:101], v[106:109], v[10:13]
	ds_read_b128 v[152:155], v142 offset:37888
	v_mfma_f32_16x16x32_bf16 v[14:17], v[102:105], v[106:109], v[14:17]
	ds_read_b128 v[156:159], v142 offset:39936
	v_mfma_f32_16x16x32_bf16 v[18:21], v[90:93], v[110:113], v[18:21]
	ds_read_b128 v[160:163], v141 offset:33792
	v_mfma_f32_16x16x32_bf16 v[22:25], v[94:97], v[110:113], v[22:25]
	ds_read_b128 v[164:167], v141 offset:35840
	v_mfma_f32_16x16x32_bf16 v[26:29], v[98:101], v[110:113], v[26:29]
	ds_read_b128 v[168:171], v141 offset:37888
	v_mfma_f32_16x16x32_bf16 v[30:33], v[102:105], v[110:113], v[30:33]
	ds_read_b128 v[172:175], v141 offset:39936
	v_mfma_f32_16x16x32_bf16 v[34:37], v[90:93], v[114:117], v[34:37]
	v_mfma_f32_16x16x32_bf16 v[38:41], v[94:97], v[114:117], v[38:41]
	v_mfma_f32_16x16x32_bf16 v[42:45], v[98:101], v[114:117], v[42:45]
	v_mfma_f32_16x16x32_bf16 v[46:49], v[102:105], v[114:117], v[46:49]
	v_mfma_f32_16x16x32_bf16 v[50:53], v[90:93], v[118:121], v[50:53]
	v_mfma_f32_16x16x32_bf16 v[54:57], v[94:97], v[118:121], v[54:57]
	v_mfma_f32_16x16x32_bf16 v[58:61], v[98:101], v[118:121], v[58:61]
	v_mfma_f32_16x16x32_bf16 v[62:65], v[102:105], v[118:121], v[62:65]
	s_waitcnt vmcnt(0) lgkmcnt(0)
	s_barrier
	v_mfma_f32_16x16x32_bf16 v[2:5], v[144:147], v[160:163], v[2:5]
	ds_read_b128 v[90:93], v142
	s_add_u32 m0, s22, 0x8000
	v_mov_b32_e32 v179, v176
	global_load_lds_dwordx4 v179, s[6:7]
	v_mfma_f32_16x16x32_bf16 v[6:9], v[148:151], v[160:163], v[6:9]
	ds_read_b128 v[94:97], v142 offset:2048
	s_add_u32 m0, s22, 0x8400
	v_add_u32_e32 v180, 0x40, v176
	global_load_lds_dwordx4 v180, s[6:7]
	v_mfma_f32_16x16x32_bf16 v[10:13], v[152:155], v[160:163], v[10:13]
	ds_read_b128 v[98:101], v142 offset:4096
	s_add_u32 m0, s22, 0x8800
	v_add_u32_e32 v179, 0x8000, v176
	global_load_lds_dwordx4 v179, s[6:7]
	v_mfma_f32_16x16x32_bf16 v[14:17], v[156:159], v[160:163], v[14:17]
	ds_read_b128 v[102:105], v142 offset:6144
	s_add_u32 m0, s22, 0x8c00
	v_add_u32_e32 v180, 0x8040, v176
	global_load_lds_dwordx4 v180, s[6:7]
	v_mfma_f32_16x16x32_bf16 v[18:21], v[144:147], v[164:167], v[18:21]
	ds_read_b128 v[106:109], v141
	s_add_u32 m0, s22, 0xc000
	v_mov_b32_e32 v179, v176
	global_load_lds_dwordx4 v179, s[8:9]
	v_mfma_f32_16x16x32_bf16 v[22:25], v[148:151], v[164:167], v[22:25]
	ds_read_b128 v[110:113], v141 offset:2048
	s_add_u32 m0, s22, 0xc400
	v_add_u32_e32 v180, 0x40, v176
	global_load_lds_dwordx4 v180, s[8:9]
	v_mfma_f32_16x16x32_bf16 v[26:29], v[152:155], v[164:167], v[26:29]
	ds_read_b128 v[114:117], v141 offset:4096
	s_add_u32 m0, s22, 0xc800
	v_add_u32_e32 v179, 0x8000, v176
	global_load_lds_dwordx4 v179, s[8:9]
	v_mfma_f32_16x16x32_bf16 v[30:33], v[156:159], v[164:167], v[30:33]
	ds_read_b128 v[118:121], v141 offset:6144
	s_add_u32 m0, s22, 0xcc00
	v_add_u32_e32 v180, 0x8040, v176
	global_load_lds_dwordx4 v180, s[8:9]
	v_mfma_f32_16x16x32_bf16 v[34:37], v[144:147], v[168:171], v[34:37]
	v_mfma_f32_16x16x32_bf16 v[38:41], v[148:151], v[168:171], v[38:41]
	v_mfma_f32_16x16x32_bf16 v[42:45], v[152:155], v[168:171], v[42:45]
	v_mfma_f32_16x16x32_bf16 v[46:49], v[156:159], v[168:171], v[46:49]
	v_mfma_f32_16x16x32_bf16 v[50:53], v[144:147], v[172:175], v[50:53]
	v_mfma_f32_16x16x32_bf16 v[54:57], v[148:151], v[172:175], v[54:57]
	v_mfma_f32_16x16x32_bf16 v[58:61], v[152:155], v[172:175], v[58:61]
	v_mfma_f32_16x16x32_bf16 v[62:65], v[156:159], v[172:175], v[62:65]
	v_add_u32_e32 v176, 0x80, v176
	s_mov_b32 s16, 6

.Lg128_wo_next_retry:
	s_cmp_ge_u32 s12, 128
	s_cbranch_scc1 .Lg128_wo_nonext
	s_lshr_b32 s3, s12, 6
	s_lshl_b32 s3, s3, 3
	s_add_u32 s3, s3, s65
	s_mov_b32 s17, s3
	s_mov_b32 s3, 0
	s_lshl_b32 s17, s17, 3
	s_bfe_u32 s23, s12, 0x30003
	s_add_u32 s13, s17, s23
	s_lshl_b32 s3, s3, 3
	s_and_b32 s23, s12, 7
	s_add_u32 s14, s3, s23
	s_lshl_b32 s13, s13, 7
	s_lshl_b32 s14, s14, 7
	s_lshl_b32 s3, s15, 5
	s_add_u32 s17, s3, s13
	s_mul_i32 s17, s17, 0x800
	s_add_u32 s6, s18, s17
	s_addc_u32 s7, s19, 0
	s_add_u32 s17, s3, s14
	s_mul_i32 s17, s17, 0x800
	s_add_u32 s8, s20, s17
	s_addc_u32 s9, s21, 0
	v_mov_b32_e32 v176, v177
	s_mov_b32 s16, 1
	s_waitcnt lgkmcnt(0)
	v_mfma_f32_16x16x32_bf16 v[2:5], v[90:93], v[106:109], v[2:5]
	ds_read_b128 v[144:147], v142 offset:1024
	v_mfma_f32_16x16x32_bf16 v[6:9], v[94:97], v[106:109], v[6:9]
	ds_read_b128 v[148:151], v142 offset:3072
	v_mfma_f32_16x16x32_bf16 v[10:13], v[98:101], v[106:109], v[10:13]
	ds_read_b128 v[152:155], v142 offset:5120
	v_mfma_f32_16x16x32_bf16 v[14:17], v[102:105], v[106:109], v[14:17]
	ds_read_b128 v[156:159], v142 offset:7168
	v_mfma_f32_16x16x32_bf16 v[18:21], v[90:93], v[110:113], v[18:21]
	ds_read_b128 v[160:163], v141 offset:1024
	v_mfma_f32_16x16x32_bf16 v[22:25], v[94:97], v[110:113], v[22:25]
	ds_read_b128 v[164:167], v141 offset:3072
	v_mfma_f32_16x16x32_bf16 v[26:29], v[98:101], v[110:113], v[26:29]
	ds_read_b128 v[168:171], v141 offset:5120
	v_mfma_f32_16x16x32_bf16 v[30:33], v[102:105], v[110:113], v[30:33]
	ds_read_b128 v[172:175], v141 offset:7168
	v_mfma_f32_16x16x32_bf16 v[34:37], v[90:93], v[114:117], v[34:37]
	v_mfma_f32_16x16x32_bf16 v[38:41], v[94:97], v[114:117], v[38:41]
	v_mfma_f32_16x16x32_bf16 v[42:45], v[98:101], v[114:117], v[42:45]
	v_mfma_f32_16x16x32_bf16 v[46:49], v[102:105], v[114:117], v[46:49]
	v_mfma_f32_16x16x32_bf16 v[50:53], v[90:93], v[118:121], v[50:53]
	v_mfma_f32_16x16x32_bf16 v[54:57], v[94:97], v[118:121], v[54:57]
	v_mfma_f32_16x16x32_bf16 v[58:61], v[98:101], v[118:121], v[58:61]
	v_mfma_f32_16x16x32_bf16 v[62:65], v[102:105], v[118:121], v[62:65]
	s_waitcnt vmcnt(0) lgkmcnt(0)
	s_barrier
	v_mfma_f32_16x16x32_bf16 v[2:5], v[144:147], v[160:163], v[2:5]
	ds_read_b128 v[90:93], v142 offset:32768
	s_add_u32 m0, s22, 0x0
	v_mov_b32_e32 v179, v176
	global_load_lds_dwordx4 v179, s[6:7]
	v_mfma_f32_16x16x32_bf16 v[6:9], v[148:151], v[160:163], v[6:9]
	ds_read_b128 v[94:97], v142 offset:34816
	s_add_u32 m0, s22, 0x400
	v_add_u32_e32 v180, 0x40, v176
	global_load_lds_dwordx4 v180, s[6:7]
	v_mfma_f32_16x16x32_bf16 v[10:13], v[152:155], v[160:163], v[10:13]
	ds_read_b128 v[98:101], v142 offset:36864
	s_add_u32 m0, s22, 0x800
	v_add_u32_e32 v179, 0x8000, v176
	global_load_lds_dwordx4 v179, s[6:7]
	v_mfma_f32_16x16x32_bf16 v[14:17], v[156:159], v[160:163], v[14:17]
	ds_read_b128 v[102:105], v142 offset:38912
	s_add_u32 m0, s22, 0xc00
	v_add_u32_e32 v180, 0x8040, v176
	global_load_lds_dwordx4 v180, s[6:7]
	v_mfma_f32_16x16x32_bf16 v[18:21], v[144:147], v[164:167], v[18:21]
	ds_read_b128 v[106:109], v141 offset:32768
	s_add_u32 m0, s22, 0x4000
	v_mov_b32_e32 v179, v176
	global_load_lds_dwordx4 v179, s[8:9]
	v_mfma_f32_16x16x32_bf16 v[22:25], v[148:151], v[164:167], v[22:25]
	ds_read_b128 v[110:113], v141 offset:34816
	s_add_u32 m0, s22, 0x4400
	v_add_u32_e32 v180, 0x40, v176
	global_load_lds_dwordx4 v180, s[8:9]
	v_mfma_f32_16x16x32_bf16 v[26:29], v[152:155], v[164:167], v[26:29]
	ds_read_b128 v[114:117], v141 offset:36864
	s_add_u32 m0, s22, 0x4800
	v_add_u32_e32 v179, 0x8000, v176
	global_load_lds_dwordx4 v179, s[8:9]
	v_mfma_f32_16x16x32_bf16 v[30:33], v[156:159], v[164:167], v[30:33]
	ds_read_b128 v[118:121], v141 offset:38912
	s_add_u32 m0, s22, 0x4c00
	v_add_u32_e32 v180, 0x8040, v176
	global_load_lds_dwordx4 v180, s[8:9]
	v_mfma_f32_16x16x32_bf16 v[34:37], v[144:147], v[168:171], v[34:37]
	v_mfma_f32_16x16x32_bf16 v[38:41], v[148:151], v[168:171], v[38:41]
	v_mfma_f32_16x16x32_bf16 v[42:45], v[152:155], v[168:171], v[42:45]
	v_mfma_f32_16x16x32_bf16 v[46:49], v[156:159], v[168:171], v[46:49]
	v_mfma_f32_16x16x32_bf16 v[50:53], v[144:147], v[172:175], v[50:53]
	v_mfma_f32_16x16x32_bf16 v[54:57], v[148:151], v[172:175], v[54:57]
	v_mfma_f32_16x16x32_bf16 v[58:61], v[152:155], v[172:175], v[58:61]
	v_mfma_f32_16x16x32_bf16 v[62:65], v[156:159], v[172:175], v[62:65]
	v_add_u32_e32 v176, 0x80, v176
	s_waitcnt lgkmcnt(0)
	v_mfma_f32_16x16x32_bf16 v[2:5], v[90:93], v[106:109], v[2:5]
	ds_read_b128 v[144:147], v142 offset:33792
	v_mfma_f32_16x16x32_bf16 v[6:9], v[94:97], v[106:109], v[6:9]
	ds_read_b128 v[148:151], v142 offset:35840
	v_mfma_f32_16x16x32_bf16 v[10:13], v[98:101], v[106:109], v[10:13]
	ds_read_b128 v[152:155], v142 offset:37888
	v_mfma_f32_16x16x32_bf16 v[14:17], v[102:105], v[106:109], v[14:17]
	ds_read_b128 v[156:159], v142 offset:39936
	v_mfma_f32_16x16x32_bf16 v[18:21], v[90:93], v[110:113], v[18:21]
	ds_read_b128 v[160:163], v141 offset:33792
	v_mfma_f32_16x16x32_bf16 v[22:25], v[94:97], v[110:113], v[22:25]
	ds_read_b128 v[164:167], v141 offset:35840
	v_mfma_f32_16x16x32_bf16 v[26:29], v[98:101], v[110:113], v[26:29]
	ds_read_b128 v[168:171], v141 offset:37888
	v_mfma_f32_16x16x32_bf16 v[30:33], v[102:105], v[110:113], v[30:33]
	ds_read_b128 v[172:175], v141 offset:39936
	v_mfma_f32_16x16x32_bf16 v[34:37], v[90:93], v[114:117], v[34:37]
	v_mfma_f32_16x16x32_bf16 v[38:41], v[94:97], v[114:117], v[38:41]
	v_mfma_f32_16x16x32_bf16 v[42:45], v[98:101], v[114:117], v[42:45]
	v_mfma_f32_16x16x32_bf16 v[46:49], v[102:105], v[114:117], v[46:49]
	v_mfma_f32_16x16x32_bf16 v[50:53], v[90:93], v[118:121], v[50:53]
	v_mfma_f32_16x16x32_bf16 v[54:57], v[94:97], v[118:121], v[54:57]
	v_mfma_f32_16x16x32_bf16 v[58:61], v[98:101], v[118:121], v[58:61]
	v_mfma_f32_16x16x32_bf16 v[62:65], v[102:105], v[118:121], v[62:65]
	s_waitcnt vmcnt(0) lgkmcnt(0)
	s_barrier
	v_mfma_f32_16x16x32_bf16 v[2:5], v[144:147], v[160:163], v[2:5]
	ds_read_b128 v[90:93], v142
	s_add_u32 m0, s22, 0x8000
	v_mov_b32_e32 v179, v176
	global_load_lds_dwordx4 v179, s[6:7]
	v_mfma_f32_16x16x32_bf16 v[6:9], v[148:151], v[160:163], v[6:9]
	ds_read_b128 v[94:97], v142 offset:2048
	s_add_u32 m0, s22, 0x8400
	v_add_u32_e32 v180, 0x40, v176
	global_load_lds_dwordx4 v180, s[6:7]
	v_mfma_f32_16x16x32_bf16 v[10:13], v[152:155], v[160:163], v[10:13]
	ds_read_b128 v[98:101], v142 offset:4096
	s_add_u32 m0, s22, 0x8800
	v_add_u32_e32 v179, 0x8000, v176
	global_load_lds_dwordx4 v179, s[6:7]
	v_mfma_f32_16x16x32_bf16 v[14:17], v[156:159], v[160:163], v[14:17]
	ds_read_b128 v[102:105], v142 offset:6144
	s_add_u32 m0, s22, 0x8c00
	v_add_u32_e32 v180, 0x8040, v176
	global_load_lds_dwordx4 v180, s[6:7]
	v_mfma_f32_16x16x32_bf16 v[18:21], v[144:147], v[164:167], v[18:21]
	ds_read_b128 v[106:109], v141
	s_add_u32 m0, s22, 0xc000
	v_mov_b32_e32 v179, v176
	global_load_lds_dwordx4 v179, s[8:9]
	v_mfma_f32_16x16x32_bf16 v[22:25], v[148:151], v[164:167], v[22:25]
	ds_read_b128 v[110:113], v141 offset:2048
	s_add_u32 m0, s22, 0xc400
	v_add_u32_e32 v180, 0x40, v176
	global_load_lds_dwordx4 v180, s[8:9]
	v_mfma_f32_16x16x32_bf16 v[26:29], v[152:155], v[164:167], v[26:29]
	ds_read_b128 v[114:117], v141 offset:4096
	s_add_u32 m0, s22, 0xc800
	v_add_u32_e32 v179, 0x8000, v176
	global_load_lds_dwordx4 v179, s[8:9]
	v_mfma_f32_16x16x32_bf16 v[30:33], v[156:159], v[164:167], v[30:33]
	ds_read_b128 v[118:121], v141 offset:6144
	s_add_u32 m0, s22, 0xcc00
	v_add_u32_e32 v180, 0x8040, v176
	global_load_lds_dwordx4 v180, s[8:9]
	v_mfma_f32_16x16x32_bf16 v[34:37], v[144:147], v[168:171], v[34:37]
	v_mfma_f32_16x16x32_bf16 v[38:41], v[148:151], v[168:171], v[38:41]
	v_mfma_f32_16x16x32_bf16 v[42:45], v[152:155], v[168:171], v[42:45]
	v_mfma_f32_16x16x32_bf16 v[46:49], v[156:159], v[168:171], v[46:49]
	v_mfma_f32_16x16x32_bf16 v[50:53], v[144:147], v[172:175], v[50:53]
	v_mfma_f32_16x16x32_bf16 v[54:57], v[148:151], v[172:175], v[54:57]
	v_mfma_f32_16x16x32_bf16 v[58:61], v[152:155], v[172:175], v[58:61]
	v_mfma_f32_16x16x32_bf16 v[62:65], v[156:159], v[172:175], v[62:65]
	v_add_u32_e32 v176, 0x80, v176
	s_branch .Lg128_wo_epi

.LBB0_805:
	s_andn2_b64 vcc, exec, s[4:5]
	s_cbranch_vccnz .LBB0_843
	v_readlane_b32 s4, v239, 13
	v_readlane_b32 s5, v239, 14
	s_andn2_b64 vcc, exec, s[4:5]
	s_cbranch_vccnz .LBB0_843
	s_load_dwordx2 s[4:5], s[0:1], 0x130
	v_and_b32_e32 v0, 63, v133
	v_lshrrev_b32_e32 v131, 6, v133
	v_lshrrev_b32_e32 v195, 2, v0
	v_readfirstlane_b32 s15, v131
	v_mul_u32_u24_e32 v177, 0x800, v195
	v_and_b32_e32 v195, 3, v0
	v_lshlrev_b32_e32 v195, 4, v195
	v_lshrrev_b32_e32 v131, 5, v0
	v_lshlrev_b32_e32 v131, 5, v131
	v_xor_b32_e32 v195, v195, v131
	v_add_u32_e32 v177, v177, v195
	v_and_b32_e32 v195, 15, v0
	v_lshrrev_b32_e32 v131, 4, v0
	v_lshlrev_b32_e32 v141, 6, v195
	v_lshl_or_b32 v141, v131, 4, v141
	v_and_b32_e32 v178, 8, v0
	v_lshlrev_b32_e32 v178, 2, v178
	v_xor_b32_e32 v141, v141, v178
	v_mul_u32_u24_e32 v178, 0x1440, v195
	v_lshl_or_b32 v178, v131, 3, v178
	s_waitcnt lgkmcnt(0)
	s_add_u32 s18, s4, 0x2b27800
	s_addc_u32 s19, s5, 0
	s_add_u32 s20, s4, 0x9e7800
	s_addc_u32 s21, s5, 0
	s_add_u32 s24, s4, 0x4b27800
	s_addc_u32 s25, s5, 0
	s_and_b32 s3, s15, 1
	s_lshl_b32 s3, s3, 13
	s_add_u32 s3, s3, 16384
	v_add_u32_e32 v142, s3, v141
	s_lshr_b32 s3, s15, 1
	s_lshl_b32 s3, s3, 13
	v_add_u32_e32 v141, s3, v141
	s_lshl_b32 s22, s15, 12
	s_mov_b32 s12, s79
	s_cmp_ge_u32 s12, 336
	s_cbranch_scc1 .Lg128_ip_done
	s_mul_i32 s3, s12, 1171
	s_lshr_b32 s3, s3, 16
	s_mul_i32 s17, s3, 56
	s_sub_u32 s23, s12, s17
	s_lshl_b32 s3, s3, 3
	s_add_u32 s3, s3, s65
	s_mul_i32 s17, s3, 43
	s_lshr_b32 s17, s17, 7
	s_mul_i32 s13, s17, 3
	s_sub_u32 s3, s3, s13
	s_mul_i32 s13, s23, 37
	s_lshr_b32 s13, s13, 8
	s_mul_i32 s14, s13, 7
	s_sub_u32 s14, s23, s14
	s_lshl_b32 s17, s17, 3
	s_add_u32 s13, s13, s17
	s_mul_i32 s3, s3, 7
	s_add_u32 s14, s14, s3
	s_lshl_b32 s13, s13, 7
	s_lshl_b32 s14, s14, 7
	s_lshl_b32 s3, s15, 5
	s_add_u32 s17, s3, s13
	s_mul_i32 s17, s17, 0x800
	s_add_u32 s6, s18, s17
	s_addc_u32 s7, s19, 0
	s_add_u32 s17, s3, s14
	s_mul_i32 s17, s17, 0x800
	s_add_u32 s8, s20, s17
	s_addc_u32 s9, s21, 0
	s_barrier
	v_mov_b32_e32 v176, v177
	s_add_u32 m0, s22, 0x0
	v_mov_b32_e32 v179, v176
	global_load_lds_dwordx4 v179, s[6:7]
	s_add_u32 m0, s22, 0x400
	v_add_u32_e32 v180, 0x40, v176
	global_load_lds_dwordx4 v180, s[6:7]
	s_add_u32 m0, s22, 0x800
	v_add_u32_e32 v179, 0x8000, v176
	global_load_lds_dwordx4 v179, s[6:7]
	s_add_u32 m0, s22, 0xc00
	v_add_u32_e32 v180, 0x8040, v176
	global_load_lds_dwordx4 v180, s[6:7]
	s_add_u32 m0, s22, 0x4000
	v_mov_b32_e32 v179, v176
	global_load_lds_dwordx4 v179, s[8:9]
	s_add_u32 m0, s22, 0x4400
	v_add_u32_e32 v180, 0x40, v176
	global_load_lds_dwordx4 v180, s[8:9]
	s_add_u32 m0, s22, 0x4800
	v_add_u32_e32 v179, 0x8000, v176
	global_load_lds_dwordx4 v179, s[8:9]
	s_add_u32 m0, s22, 0x4c00
	v_add_u32_e32 v180, 0x8040, v176
	global_load_lds_dwordx4 v180, s[8:9]
	v_add_u32_e32 v176, 0x80, v176
	s_add_u32 m0, s22, 0x8000
	v_mov_b32_e32 v179, v176
	global_load_lds_dwordx4 v179, s[6:7]
	s_add_u32 m0, s22, 0x8400
	v_add_u32_e32 v180, 0x40, v176
	global_load_lds_dwordx4 v180, s[6:7]
	s_add_u32 m0, s22, 0x8800
	v_add_u32_e32 v179, 0x8000, v176
	global_load_lds_dwordx4 v179, s[6:7]
	s_add_u32 m0, s22, 0x8c00
	v_add_u32_e32 v180, 0x8040, v176
	global_load_lds_dwordx4 v180, s[6:7]
	s_add_u32 m0, s22, 0xc000
	v_mov_b32_e32 v179, v176
	global_load_lds_dwordx4 v179, s[8:9]
	s_add_u32 m0, s22, 0xc400
	v_add_u32_e32 v180, 0x40, v176
	global_load_lds_dwordx4 v180, s[8:9]
	s_add_u32 m0, s22, 0xc800
	v_add_u32_e32 v179, 0x8000, v176
	global_load_lds_dwordx4 v179, s[8:9]
	s_add_u32 m0, s22, 0xcc00
	v_add_u32_e32 v180, 0x8040, v176
	global_load_lds_dwordx4 v180, s[8:9]
	v_add_u32_e32 v176, 0x80, v176
	s_waitcnt vmcnt(0)
	s_barrier
	ds_read_b128 v[90:93], v142
	ds_read_b128 v[94:97], v142 offset:2048
	ds_read_b128 v[98:101], v142 offset:4096
	ds_read_b128 v[102:105], v142 offset:6144
	ds_read_b128 v[106:109], v141
	ds_read_b128 v[110:113], v141 offset:2048
	ds_read_b128 v[114:117], v141 offset:4096
	ds_read_b128 v[118:121], v141 offset:6144
.Lg128_ip_tile:
	s_lshr_b32 s3, s15, 1
	s_lshl_b32 s3, s3, 6
	s_add_u32 s3, s3, s13
	s_mul_i32 s17, s3, 0x1440
	s_and_b32 s3, s15, 1
	s_lshl_b32 s3, s3, 6
	s_add_u32 s3, s3, s14
	s_mul_i32 s3, s3, 2
	s_add_u32 s17, s17, s3
	s_add_u32 s10, s24, s17
	s_addc_u32 s11, s25, 0
	s_cmp_eq_u32 s14, 2560
	s_cselect_b32 s27, 1, 0
	s_waitcnt lgkmcnt(0)
	v_mfma_f32_16x16x32_bf16 v[2:5], v[90:93], v[106:109], 0
	ds_read_b128 v[144:147], v142 offset:1024
	v_mfma_f32_16x16x32_bf16 v[6:9], v[94:97], v[106:109], 0
	ds_read_b128 v[148:151], v142 offset:3072
	v_mfma_f32_16x16x32_bf16 v[10:13], v[98:101], v[106:109], 0
	ds_read_b128 v[152:155], v142 offset:5120
	v_mfma_f32_16x16x32_bf16 v[14:17], v[102:105], v[106:109], 0
	ds_read_b128 v[156:159], v142 offset:7168
	v_mfma_f32_16x16x32_bf16 v[18:21], v[90:93], v[110:113], 0
	ds_read_b128 v[160:163], v141 offset:1024
	v_mfma_f32_16x16x32_bf16 v[22:25], v[94:97], v[110:113], 0
	ds_read_b128 v[164:167], v141 offset:3072
	v_mfma_f32_16x16x32_bf16 v[26:29], v[98:101], v[110:113], 0
	ds_read_b128 v[168:171], v141 offset:5120
	v_mfma_f32_16x16x32_bf16 v[30:33], v[102:105], v[110:113], 0
	ds_read_b128 v[172:175], v141 offset:7168
	v_mfma_f32_16x16x32_bf16 v[34:37], v[90:93], v[114:117], 0
	v_mfma_f32_16x16x32_bf16 v[38:41], v[94:97], v[114:117], 0
	v_mfma_f32_16x16x32_bf16 v[42:45], v[98:101], v[114:117], 0
	v_mfma_f32_16x16x32_bf16 v[46:49], v[102:105], v[114:117], 0
	v_mfma_f32_16x16x32_bf16 v[50:53], v[90:93], v[118:121], 0
	v_mfma_f32_16x16x32_bf16 v[54:57], v[94:97], v[118:121], 0
	v_mfma_f32_16x16x32_bf16 v[58:61], v[98:101], v[118:121], 0
	v_mfma_f32_16x16x32_bf16 v[62:65], v[102:105], v[118:121], 0
	s_waitcnt vmcnt(0) lgkmcnt(0)
	s_barrier
	v_mfma_f32_16x16x32_bf16 v[2:5], v[144:147], v[160:163], v[2:5]
	ds_read_b128 v[90:93], v142 offset:32768
	s_add_u32 m0, s22, 0x0
	v_mov_b32_e32 v179, v176
	global_load_lds_dwordx4 v179, s[6:7]
	v_mfma_f32_16x16x32_bf16 v[6:9], v[148:151], v[160:163], v[6:9]
	ds_read_b128 v[94:97], v142 offset:34816
	s_add_u32 m0, s22, 0x400
	v_add_u32_e32 v180, 0x40, v176
	global_load_lds_dwordx4 v180, s[6:7]
	v_mfma_f32_16x16x32_bf16 v[10:13], v[152:155], v[160:163], v[10:13]
	ds_read_b128 v[98:101], v142 offset:36864
	s_add_u32 m0, s22, 0x800
	v_add_u32_e32 v179, 0x8000, v176
	global_load_lds_dwordx4 v179, s[6:7]
	v_mfma_f32_16x16x32_bf16 v[14:17], v[156:159], v[160:163], v[14:17]
	ds_read_b128 v[102:105], v142 offset:38912
	s_add_u32 m0, s22, 0xc00
	v_add_u32_e32 v180, 0x8040, v176
	global_load_lds_dwordx4 v180, s[6:7]
	v_mfma_f32_16x16x32_bf16 v[18:21], v[144:147], v[164:167], v[18:21]
	ds_read_b128 v[106:109], v141 offset:32768
	s_add_u32 m0, s22, 0x4000
	v_mov_b32_e32 v179, v176
	global_load_lds_dwordx4 v179, s[8:9]
	v_mfma_f32_16x16x32_bf16 v[22:25], v[148:151], v[164:167], v[22:25]
	ds_read_b128 v[110:113], v141 offset:34816
	s_add_u32 m0, s22, 0x4400
	v_add_u32_e32 v180, 0x40, v176
	global_load_lds_dwordx4 v180, s[8:9]
	v_mfma_f32_16x16x32_bf16 v[26:29], v[152:155], v[164:167], v[26:29]
	ds_read_b128 v[114:117], v141 offset:36864
	s_add_u32 m0, s22, 0x4800
	v_add_u32_e32 v179, 0x8000, v176
	global_load_lds_dwordx4 v179, s[8:9]
	v_mfma_f32_16x16x32_bf16 v[30:33], v[156:159], v[164:167], v[30:33]
	ds_read_b128 v[118:121], v141 offset:38912
	s_add_u32 m0, s22, 0x4c00
	v_add_u32_e32 v180, 0x8040, v176
	global_load_lds_dwordx4 v180, s[8:9]
	v_mfma_f32_16x16x32_bf16 v[34:37], v[144:147], v[168:171], v[34:37]
	v_mfma_f32_16x16x32_bf16 v[38:41], v[148:151], v[168:171], v[38:41]
	v_mfma_f32_16x16x32_bf16 v[42:45], v[152:155], v[168:171], v[42:45]
	v_mfma_f32_16x16x32_bf16 v[46:49], v[156:159], v[168:171], v[46:49]
	v_mfma_f32_16x16x32_bf16 v[50:53], v[144:147], v[172:175], v[50:53]
	v_mfma_f32_16x16x32_bf16 v[54:57], v[148:151], v[172:175], v[54:57]
	v_mfma_f32_16x16x32_bf16 v[58:61], v[152:155], v[172:175], v[58:61]
	v_mfma_f32_16x16x32_bf16 v[62:65], v[156:159], v[172:175], v[62:65]
	v_add_u32_e32 v176, 0x80, v176
	s_waitcnt lgkmcnt(0)
	v_mfma_f32_16x16x32_bf16 v[2:5], v[90:93], v[106:109], v[2:5]
	ds_read_b128 v[144:147], v142 offset:33792
	v_mfma_f32_16x16x32_bf16 v[6:9], v[94:97], v[106:109], v[6:9]
	ds_read_b128 v[148:151], v142 offset:35840
	v_mfma_f32_16x16x32_bf16 v[10:13], v[98:101], v[106:109], v[10:13]
	ds_read_b128 v[152:155], v142 offset:37888
	v_mfma_f32_16x16x32_bf16 v[14:17], v[102:105], v[106:109], v[14:17]
	ds_read_b128 v[156:159], v142 offset:39936
	v_mfma_f32_16x16x32_bf16 v[18:21], v[90:93], v[110:113], v[18:21]
	ds_read_b128 v[160:163], v141 offset:33792
	v_mfma_f32_16x16x32_bf16 v[22:25], v[94:97], v[110:113], v[22:25]
	ds_read_b128 v[164:167], v141 offset:35840
	v_mfma_f32_16x16x32_bf16 v[26:29], v[98:101], v[110:113], v[26:29]
	ds_read_b128 v[168:171], v141 offset:37888
	v_mfma_f32_16x16x32_bf16 v[30:33], v[102:105], v[110:113], v[30:33]
	ds_read_b128 v[172:175], v141 offset:39936
	v_mfma_f32_16x16x32_bf16 v[34:37], v[90:93], v[114:117], v[34:37]
	v_mfma_f32_16x16x32_bf16 v[38:41], v[94:97], v[114:117], v[38:41]
	v_mfma_f32_16x16x32_bf16 v[42:45], v[98:101], v[114:117], v[42:45]
	v_mfma_f32_16x16x32_bf16 v[46:49], v[102:105], v[114:117], v[46:49]
	v_mfma_f32_16x16x32_bf16 v[50:53], v[90:93], v[118:121], v[50:53]
	v_mfma_f32_16x16x32_bf16 v[54:57], v[94:97], v[118:121], v[54:57]
	v_mfma_f32_16x16x32_bf16 v[58:61], v[98:101], v[118:121], v[58:61]
	v_mfma_f32_16x16x32_bf16 v[62:65], v[102:105], v[118:121], v[62:65]
	s_waitcnt vmcnt(0) lgkmcnt(0)
	s_barrier
	v_mfma_f32_16x16x32_bf16 v[2:5], v[144:147], v[160:163], v[2:5]
	ds_read_b128 v[90:93], v142
	s_add_u32 m0, s22, 0x8000
	v_mov_b32_e32 v179, v176
	global_load_lds_dwordx4 v179, s[6:7]
	v_mfma_f32_16x16x32_bf16 v[6:9], v[148:151], v[160:163], v[6:9]
	ds_read_b128 v[94:97], v142 offset:2048
	s_add_u32 m0, s22, 0x8400
	v_add_u32_e32 v180, 0x40, v176
	global_load_lds_dwordx4 v180, s[6:7]
	v_mfma_f32_16x16x32_bf16 v[10:13], v[152:155], v[160:163], v[10:13]
	ds_read_b128 v[98:101], v142 offset:4096
	s_add_u32 m0, s22, 0x8800
	v_add_u32_e32 v179, 0x8000, v176
	global_load_lds_dwordx4 v179, s[6:7]
	v_mfma_f32_16x16x32_bf16 v[14:17], v[156:159], v[160:163], v[14:17]
	ds_read_b128 v[102:105], v142 offset:6144
	s_add_u32 m0, s22, 0x8c00
	v_add_u32_e32 v180, 0x8040, v176
	global_load_lds_dwordx4 v180, s[6:7]
	v_mfma_f32_16x16x32_bf16 v[18:21], v[144:147], v[164:167], v[18:21]
	ds_read_b128 v[106:109], v141
	s_add_u32 m0, s22, 0xc000
	v_mov_b32_e32 v179, v176
	global_load_lds_dwordx4 v179, s[8:9]
	v_mfma_f32_16x16x32_bf16 v[22:25], v[148:151], v[164:167], v[22:25]
	ds_read_b128 v[110:113], v141 offset:2048
	s_add_u32 m0, s22, 0xc400
	v_add_u32_e32 v180, 0x40, v176
	global_load_lds_dwordx4 v180, s[8:9]
	v_mfma_f32_16x16x32_bf16 v[26:29], v[152:155], v[164:167], v[26:29]
	ds_read_b128 v[114:117], v141 offset:4096
	s_add_u32 m0, s22, 0xc800
	v_add_u32_e32 v179, 0x8000, v176
	global_load_lds_dwordx4 v179, s[8:9]
	v_mfma_f32_16x16x32_bf16 v[30:33], v[156:159], v[164:167], v[30:33]
	ds_read_b128 v[118:121], v141 offset:6144
	s_add_u32 m0, s22, 0xcc00
	v_add_u32_e32 v180, 0x8040, v176
	global_load_lds_dwordx4 v180, s[8:9]
	v_mfma_f32_16x16x32_bf16 v[34:37], v[144:147], v[168:171], v[34:37]
	v_mfma_f32_16x16x32_bf16 v[38:41], v[148:151], v[168:171], v[38:41]
	v_mfma_f32_16x16x32_bf16 v[42:45], v[152:155], v[168:171], v[42:45]
	v_mfma_f32_16x16x32_bf16 v[46:49], v[156:159], v[168:171], v[46:49]
	v_mfma_f32_16x16x32_bf16 v[50:53], v[144:147], v[172:175], v[50:53]
	v_mfma_f32_16x16x32_bf16 v[54:57], v[148:151], v[172:175], v[54:57]
	v_mfma_f32_16x16x32_bf16 v[58:61], v[152:155], v[172:175], v[58:61]
	v_mfma_f32_16x16x32_bf16 v[62:65], v[156:159], v[172:175], v[62:65]
	v_add_u32_e32 v176, 0x80, v176
	s_mov_b32 s16, 6
.Lg128_ip_loop:
	s_waitcnt lgkmcnt(0)
	v_mfma_f32_16x16x32_bf16 v[2:5], v[90:93], v[106:109], v[2:5]
	ds_read_b128 v[144:147], v142 offset:1024
	v_mfma_f32_16x16x32_bf16 v[6:9], v[94:97], v[106:109], v[6:9]
	ds_read_b128 v[148:151], v142 offset:3072
	v_mfma_f32_16x16x32_bf16 v[10:13], v[98:101], v[106:109], v[10:13]
	ds_read_b128 v[152:155], v142 offset:5120
	v_mfma_f32_16x16x32_bf16 v[14:17], v[102:105], v[106:109], v[14:17]
	ds_read_b128 v[156:159], v142 offset:7168
	v_mfma_f32_16x16x32_bf16 v[18:21], v[90:93], v[110:113], v[18:21]
	ds_read_b128 v[160:163], v141 offset:1024
	v_mfma_f32_16x16x32_bf16 v[22:25], v[94:97], v[110:113], v[22:25]
	ds_read_b128 v[164:167], v141 offset:3072
	v_mfma_f32_16x16x32_bf16 v[26:29], v[98:101], v[110:113], v[26:29]
	ds_read_b128 v[168:171], v141 offset:5120
	v_mfma_f32_16x16x32_bf16 v[30:33], v[102:105], v[110:113], v[30:33]
	ds_read_b128 v[172:175], v141 offset:7168
	v_mfma_f32_16x16x32_bf16 v[34:37], v[90:93], v[114:117], v[34:37]
	v_mfma_f32_16x16x32_bf16 v[38:41], v[94:97], v[114:117], v[38:41]
	v_mfma_f32_16x16x32_bf16 v[42:45], v[98:101], v[114:117], v[42:45]
	v_mfma_f32_16x16x32_bf16 v[46:49], v[102:105], v[114:117], v[46:49]
	v_mfma_f32_16x16x32_bf16 v[50:53], v[90:93], v[118:121], v[50:53]
	v_mfma_f32_16x16x32_bf16 v[54:57], v[94:97], v[118:121], v[54:57]
	v_mfma_f32_16x16x32_bf16 v[58:61], v[98:101], v[118:121], v[58:61]
	v_mfma_f32_16x16x32_bf16 v[62:65], v[102:105], v[118:121], v[62:65]
	s_waitcnt vmcnt(0) lgkmcnt(0)
	s_barrier
	v_mfma_f32_16x16x32_bf16 v[2:5], v[144:147], v[160:163], v[2:5]
	ds_read_b128 v[90:93], v142 offset:32768
	s_add_u32 m0, s22, 0x0
	v_mov_b32_e32 v179, v176
	global_load_lds_dwordx4 v179, s[6:7]
	v_mfma_f32_16x16x32_bf16 v[6:9], v[148:151], v[160:163], v[6:9]
	ds_read_b128 v[94:97], v142 offset:34816
	s_add_u32 m0, s22, 0x400
	v_add_u32_e32 v180, 0x40, v176
	global_load_lds_dwordx4 v180, s[6:7]
	v_mfma_f32_16x16x32_bf16 v[10:13], v[152:155], v[160:163], v[10:13]
	ds_read_b128 v[98:101], v142 offset:36864
	s_add_u32 m0, s22, 0x800
	v_add_u32_e32 v179, 0x8000, v176
	global_load_lds_dwordx4 v179, s[6:7]
	v_mfma_f32_16x16x32_bf16 v[14:17], v[156:159], v[160:163], v[14:17]
	ds_read_b128 v[102:105], v142 offset:38912
	s_add_u32 m0, s22, 0xc00
	v_add_u32_e32 v180, 0x8040, v176
	global_load_lds_dwordx4 v180, s[6:7]
	v_mfma_f32_16x16x32_bf16 v[18:21], v[144:147], v[164:167], v[18:21]
	ds_read_b128 v[106:109], v141 offset:32768
	s_add_u32 m0, s22, 0x4000
	v_mov_b32_e32 v179, v176
	global_load_lds_dwordx4 v179, s[8:9]
	v_mfma_f32_16x16x32_bf16 v[22:25], v[148:151], v[164:167], v[22:25]
	ds_read_b128 v[110:113], v141 offset:34816
	s_add_u32 m0, s22, 0x4400
	v_add_u32_e32 v180, 0x40, v176
	global_load_lds_dwordx4 v180, s[8:9]
	v_mfma_f32_16x16x32_bf16 v[26:29], v[152:155], v[164:167], v[26:29]
	ds_read_b128 v[114:117], v141 offset:36864
	s_add_u32 m0, s22, 0x4800
	v_add_u32_e32 v179, 0x8000, v176
	global_load_lds_dwordx4 v179, s[8:9]
	v_mfma_f32_16x16x32_bf16 v[30:33], v[156:159], v[164:167], v[30:33]
	ds_read_b128 v[118:121], v141 offset:38912
	s_add_u32 m0, s22, 0x4c00
	v_add_u32_e32 v180, 0x8040, v176
	global_load_lds_dwordx4 v180, s[8:9]
	v_mfma_f32_16x16x32_bf16 v[34:37], v[144:147], v[168:171], v[34:37]
	v_mfma_f32_16x16x32_bf16 v[38:41], v[148:151], v[168:171], v[38:41]
	v_mfma_f32_16x16x32_bf16 v[42:45], v[152:155], v[168:171], v[42:45]
	v_mfma_f32_16x16x32_bf16 v[46:49], v[156:159], v[168:171], v[46:49]
	v_mfma_f32_16x16x32_bf16 v[50:53], v[144:147], v[172:175], v[50:53]
	v_mfma_f32_16x16x32_bf16 v[54:57], v[148:151], v[172:175], v[54:57]
	v_mfma_f32_16x16x32_bf16 v[58:61], v[152:155], v[172:175], v[58:61]
	v_mfma_f32_16x16x32_bf16 v[62:65], v[156:159], v[172:175], v[62:65]
	v_add_u32_e32 v176, 0x80, v176
	s_waitcnt lgkmcnt(0)
	v_mfma_f32_16x16x32_bf16 v[2:5], v[90:93], v[106:109], v[2:5]
	ds_read_b128 v[144:147], v142 offset:33792
	v_mfma_f32_16x16x32_bf16 v[6:9], v[94:97], v[106:109], v[6:9]
	ds_read_b128 v[148:151], v142 offset:35840
	v_mfma_f32_16x16x32_bf16 v[10:13], v[98:101], v[106:109], v[10:13]
	ds_read_b128 v[152:155], v142 offset:37888
	v_mfma_f32_16x16x32_bf16 v[14:17], v[102:105], v[106:109], v[14:17]
	ds_read_b128 v[156:159], v142 offset:39936
	v_mfma_f32_16x16x32_bf16 v[18:21], v[90:93], v[110:113], v[18:21]
	ds_read_b128 v[160:163], v141 offset:33792
	v_mfma_f32_16x16x32_bf16 v[22:25], v[94:97], v[110:113], v[22:25]
	ds_read_b128 v[164:167], v141 offset:35840
	v_mfma_f32_16x16x32_bf16 v[26:29], v[98:101], v[110:113], v[26:29]
	ds_read_b128 v[168:171], v141 offset:37888
	v_mfma_f32_16x16x32_bf16 v[30:33], v[102:105], v[110:113], v[30:33]
	ds_read_b128 v[172:175], v141 offset:39936
	v_mfma_f32_16x16x32_bf16 v[34:37], v[90:93], v[114:117], v[34:37]
	v_mfma_f32_16x16x32_bf16 v[38:41], v[94:97], v[114:117], v[38:41]
	v_mfma_f32_16x16x32_bf16 v[42:45], v[98:101], v[114:117], v[42:45]
	v_mfma_f32_16x16x32_bf16 v[46:49], v[102:105], v[114:117], v[46:49]
	v_mfma_f32_16x16x32_bf16 v[50:53], v[90:93], v[118:121], v[50:53]
	v_mfma_f32_16x16x32_bf16 v[54:57], v[94:97], v[118:121], v[54:57]
	v_mfma_f32_16x16x32_bf16 v[58:61], v[98:101], v[118:121], v[58:61]
	v_mfma_f32_16x16x32_bf16 v[62:65], v[102:105], v[118:121], v[62:65]
	s_waitcnt vmcnt(0) lgkmcnt(0)
	s_barrier
	v_mfma_f32_16x16x32_bf16 v[2:5], v[144:147], v[160:163], v[2:5]
	ds_read_b128 v[90:93], v142
	s_add_u32 m0, s22, 0x8000
	v_mov_b32_e32 v179, v176
	global_load_lds_dwordx4 v179, s[6:7]
	v_mfma_f32_16x16x32_bf16 v[6:9], v[148:151], v[160:163], v[6:9]
	ds_read_b128 v[94:97], v142 offset:2048
	s_add_u32 m0, s22, 0x8400
	v_add_u32_e32 v180, 0x40, v176
	global_load_lds_dwordx4 v180, s[6:7]
	v_mfma_f32_16x16x32_bf16 v[10:13], v[152:155], v[160:163], v[10:13]
	ds_read_b128 v[98:101], v142 offset:4096
	s_add_u32 m0, s22, 0x8800
	v_add_u32_e32 v179, 0x8000, v176
	global_load_lds_dwordx4 v179, s[6:7]
	v_mfma_f32_16x16x32_bf16 v[14:17], v[156:159], v[160:163], v[14:17]
	ds_read_b128 v[102:105], v142 offset:6144
	s_add_u32 m0, s22, 0x8c00
	v_add_u32_e32 v180, 0x8040, v176
	global_load_lds_dwordx4 v180, s[6:7]
	v_mfma_f32_16x16x32_bf16 v[18:21], v[144:147], v[164:167], v[18:21]
	ds_read_b128 v[106:109], v141
	s_add_u32 m0, s22, 0xc000
	v_mov_b32_e32 v179, v176
	global_load_lds_dwordx4 v179, s[8:9]
	v_mfma_f32_16x16x32_bf16 v[22:25], v[148:151], v[164:167], v[22:25]
	ds_read_b128 v[110:113], v141 offset:2048
	s_add_u32 m0, s22, 0xc400
	v_add_u32_e32 v180, 0x40, v176
	global_load_lds_dwordx4 v180, s[8:9]
	v_mfma_f32_16x16x32_bf16 v[26:29], v[152:155], v[164:167], v[26:29]
	ds_read_b128 v[114:117], v141 offset:4096
	s_add_u32 m0, s22, 0xc800
	v_add_u32_e32 v179, 0x8000, v176
	global_load_lds_dwordx4 v179, s[8:9]
	v_mfma_f32_16x16x32_bf16 v[30:33], v[156:159], v[164:167], v[30:33]
	ds_read_b128 v[118:121], v141 offset:6144
	s_add_u32 m0, s22, 0xcc00
	v_add_u32_e32 v180, 0x8040, v176
	global_load_lds_dwordx4 v180, s[8:9]
	v_mfma_f32_16x16x32_bf16 v[34:37], v[144:147], v[168:171], v[34:37]
	v_mfma_f32_16x16x32_bf16 v[38:41], v[148:151], v[168:171], v[38:41]
	v_mfma_f32_16x16x32_bf16 v[42:45], v[152:155], v[168:171], v[42:45]
	v_mfma_f32_16x16x32_bf16 v[46:49], v[156:159], v[168:171], v[46:49]
	v_mfma_f32_16x16x32_bf16 v[50:53], v[144:147], v[172:175], v[50:53]
	v_mfma_f32_16x16x32_bf16 v[54:57], v[148:151], v[172:175], v[54:57]
	v_mfma_f32_16x16x32_bf16 v[58:61], v[152:155], v[172:175], v[58:61]
	v_mfma_f32_16x16x32_bf16 v[62:65], v[156:159], v[172:175], v[62:65]
	v_add_u32_e32 v176, 0x80, v176
	s_sub_u32 s16, s16, 1
	s_cmp_lg_u32 s16, 0
	s_cbranch_scc1 .Lg128_ip_loop
	s_add_u32 s12, s12, s83
	s_cmp_ge_u32 s12, 336
	s_cbranch_scc1 .Lg128_ip_nonext
	s_mul_i32 s3, s12, 1171
	s_lshr_b32 s3, s3, 16
	s_mul_i32 s17, s3, 56
	s_sub_u32 s23, s12, s17
	s_lshl_b32 s3, s3, 3
	s_add_u32 s3, s3, s65
	s_mul_i32 s17, s3, 43
	s_lshr_b32 s17, s17, 7
	s_mul_i32 s13, s17, 3
	s_sub_u32 s3, s3, s13
	s_mul_i32 s13, s23, 37
	s_lshr_b32 s13, s13, 8
	s_mul_i32 s14, s13, 7
	s_sub_u32 s14, s23, s14
	s_lshl_b32 s17, s17, 3
	s_add_u32 s13, s13, s17
	s_mul_i32 s3, s3, 7
	s_add_u32 s14, s14, s3
	s_lshl_b32 s13, s13, 7
	s_lshl_b32 s14, s14, 7
	s_lshl_b32 s3, s15, 5
	s_add_u32 s17, s3, s13
	s_mul_i32 s17, s17, 0x800
	s_add_u32 s6, s18, s17
	s_addc_u32 s7, s19, 0
	s_add_u32 s17, s3, s14
	s_mul_i32 s17, s17, 0x800
	s_add_u32 s8, s20, s17
	s_addc_u32 s9, s21, 0
	v_mov_b32_e32 v176, v177
	s_mov_b32 s16, 1
	s_waitcnt lgkmcnt(0)
	v_mfma_f32_16x16x32_bf16 v[2:5], v[90:93], v[106:109], v[2:5]
	ds_read_b128 v[144:147], v142 offset:1024
	v_mfma_f32_16x16x32_bf16 v[6:9], v[94:97], v[106:109], v[6:9]
	ds_read_b128 v[148:151], v142 offset:3072
	v_mfma_f32_16x16x32_bf16 v[10:13], v[98:101], v[106:109], v[10:13]
	ds_read_b128 v[152:155], v142 offset:5120
	v_mfma_f32_16x16x32_bf16 v[14:17], v[102:105], v[106:109], v[14:17]
	ds_read_b128 v[156:159], v142 offset:7168
	v_mfma_f32_16x16x32_bf16 v[18:21], v[90:93], v[110:113], v[18:21]
	ds_read_b128 v[160:163], v141 offset:1024
	v_mfma_f32_16x16x32_bf16 v[22:25], v[94:97], v[110:113], v[22:25]
	ds_read_b128 v[164:167], v141 offset:3072
	v_mfma_f32_16x16x32_bf16 v[26:29], v[98:101], v[110:113], v[26:29]
	ds_read_b128 v[168:171], v141 offset:5120
	v_mfma_f32_16x16x32_bf16 v[30:33], v[102:105], v[110:113], v[30:33]
	ds_read_b128 v[172:175], v141 offset:7168
	v_mfma_f32_16x16x32_bf16 v[34:37], v[90:93], v[114:117], v[34:37]
	v_mfma_f32_16x16x32_bf16 v[38:41], v[94:97], v[114:117], v[38:41]
	v_mfma_f32_16x16x32_bf16 v[42:45], v[98:101], v[114:117], v[42:45]
	v_mfma_f32_16x16x32_bf16 v[46:49], v[102:105], v[114:117], v[46:49]
	v_mfma_f32_16x16x32_bf16 v[50:53], v[90:93], v[118:121], v[50:53]
	v_mfma_f32_16x16x32_bf16 v[54:57], v[94:97], v[118:121], v[54:57]
	v_mfma_f32_16x16x32_bf16 v[58:61], v[98:101], v[118:121], v[58:61]
	v_mfma_f32_16x16x32_bf16 v[62:65], v[102:105], v[118:121], v[62:65]
	s_waitcnt vmcnt(0) lgkmcnt(0)
	s_barrier
	v_mfma_f32_16x16x32_bf16 v[2:5], v[144:147], v[160:163], v[2:5]
	ds_read_b128 v[90:93], v142 offset:32768
	s_add_u32 m0, s22, 0x0
	v_mov_b32_e32 v179, v176
	global_load_lds_dwordx4 v179, s[6:7]
	v_mfma_f32_16x16x32_bf16 v[6:9], v[148:151], v[160:163], v[6:9]
	ds_read_b128 v[94:97], v142 offset:34816
	s_add_u32 m0, s22, 0x400
	v_add_u32_e32 v180, 0x40, v176
	global_load_lds_dwordx4 v180, s[6:7]
	v_mfma_f32_16x16x32_bf16 v[10:13], v[152:155], v[160:163], v[10:13]
	ds_read_b128 v[98:101], v142 offset:36864
	s_add_u32 m0, s22, 0x800
	v_add_u32_e32 v179, 0x8000, v176
	global_load_lds_dwordx4 v179, s[6:7]
	v_mfma_f32_16x16x32_bf16 v[14:17], v[156:159], v[160:163], v[14:17]
	ds_read_b128 v[102:105], v142 offset:38912
	s_add_u32 m0, s22, 0xc00
	v_add_u32_e32 v180, 0x8040, v176
	global_load_lds_dwordx4 v180, s[6:7]
	v_mfma_f32_16x16x32_bf16 v[18:21], v[144:147], v[164:167], v[18:21]
	ds_read_b128 v[106:109], v141 offset:32768
	s_add_u32 m0, s22, 0x4000
	v_mov_b32_e32 v179, v176
	global_load_lds_dwordx4 v179, s[8:9]
	v_mfma_f32_16x16x32_bf16 v[22:25], v[148:151], v[164:167], v[22:25]
	ds_read_b128 v[110:113], v141 offset:34816
	s_add_u32 m0, s22, 0x4400
	v_add_u32_e32 v180, 0x40, v176
	global_load_lds_dwordx4 v180, s[8:9]
	v_mfma_f32_16x16x32_bf16 v[26:29], v[152:155], v[164:167], v[26:29]
	ds_read_b128 v[114:117], v141 offset:36864
	s_add_u32 m0, s22, 0x4800
	v_add_u32_e32 v179, 0x8000, v176
	global_load_lds_dwordx4 v179, s[8:9]
	v_mfma_f32_16x16x32_bf16 v[30:33], v[156:159], v[164:167], v[30:33]
	ds_read_b128 v[118:121], v141 offset:38912
	s_add_u32 m0, s22, 0x4c00
	v_add_u32_e32 v180, 0x8040, v176
	global_load_lds_dwordx4 v180, s[8:9]
	v_mfma_f32_16x16x32_bf16 v[34:37], v[144:147], v[168:171], v[34:37]
	v_mfma_f32_16x16x32_bf16 v[38:41], v[148:151], v[168:171], v[38:41]
	v_mfma_f32_16x16x32_bf16 v[42:45], v[152:155], v[168:171], v[42:45]
	v_mfma_f32_16x16x32_bf16 v[46:49], v[156:159], v[168:171], v[46:49]
	v_mfma_f32_16x16x32_bf16 v[50:53], v[144:147], v[172:175], v[50:53]
	v_mfma_f32_16x16x32_bf16 v[54:57], v[148:151], v[172:175], v[54:57]
	v_mfma_f32_16x16x32_bf16 v[58:61], v[152:155], v[172:175], v[58:61]
	v_mfma_f32_16x16x32_bf16 v[62:65], v[156:159], v[172:175], v[62:65]
	v_add_u32_e32 v176, 0x80, v176
	s_waitcnt lgkmcnt(0)
	v_mfma_f32_16x16x32_bf16 v[2:5], v[90:93], v[106:109], v[2:5]
	ds_read_b128 v[144:147], v142 offset:33792
	v_mfma_f32_16x16x32_bf16 v[6:9], v[94:97], v[106:109], v[6:9]
	ds_read_b128 v[148:151], v142 offset:35840
	v_mfma_f32_16x16x32_bf16 v[10:13], v[98:101], v[106:109], v[10:13]
	ds_read_b128 v[152:155], v142 offset:37888
	v_mfma_f32_16x16x32_bf16 v[14:17], v[102:105], v[106:109], v[14:17]
	ds_read_b128 v[156:159], v142 offset:39936
	v_mfma_f32_16x16x32_bf16 v[18:21], v[90:93], v[110:113], v[18:21]
	ds_read_b128 v[160:163], v141 offset:33792
	v_mfma_f32_16x16x32_bf16 v[22:25], v[94:97], v[110:113], v[22:25]
	ds_read_b128 v[164:167], v141 offset:35840
	v_mfma_f32_16x16x32_bf16 v[26:29], v[98:101], v[110:113], v[26:29]
	ds_read_b128 v[168:171], v141 offset:37888
	v_mfma_f32_16x16x32_bf16 v[30:33], v[102:105], v[110:113], v[30:33]
	ds_read_b128 v[172:175], v141 offset:39936
	v_mfma_f32_16x16x32_bf16 v[34:37], v[90:93], v[114:117], v[34:37]
	v_mfma_f32_16x16x32_bf16 v[38:41], v[94:97], v[114:117], v[38:41]
	v_mfma_f32_16x16x32_bf16 v[42:45], v[98:101], v[114:117], v[42:45]
	v_mfma_f32_16x16x32_bf16 v[46:49], v[102:105], v[114:117], v[46:49]
	v_mfma_f32_16x16x32_bf16 v[50:53], v[90:93], v[118:121], v[50:53]
	v_mfma_f32_16x16x32_bf16 v[54:57], v[94:97], v[118:121], v[54:57]
	v_mfma_f32_16x16x32_bf16 v[58:61], v[98:101], v[118:121], v[58:61]
	v_mfma_f32_16x16x32_bf16 v[62:65], v[102:105], v[118:121], v[62:65]
	s_waitcnt vmcnt(0) lgkmcnt(0)
	s_barrier
	v_mfma_f32_16x16x32_bf16 v[2:5], v[144:147], v[160:163], v[2:5]
	ds_read_b128 v[90:93], v142
	s_add_u32 m0, s22, 0x8000
	v_mov_b32_e32 v179, v176
	global_load_lds_dwordx4 v179, s[6:7]
	v_mfma_f32_16x16x32_bf16 v[6:9], v[148:151], v[160:163], v[6:9]
	ds_read_b128 v[94:97], v142 offset:2048
	s_add_u32 m0, s22, 0x8400
	v_add_u32_e32 v180, 0x40, v176
	global_load_lds_dwordx4 v180, s[6:7]
	v_mfma_f32_16x16x32_bf16 v[10:13], v[152:155], v[160:163], v[10:13]
	ds_read_b128 v[98:101], v142 offset:4096
	s_add_u32 m0, s22, 0x8800
	v_add_u32_e32 v179, 0x8000, v176
	global_load_lds_dwordx4 v179, s[6:7]
	v_mfma_f32_16x16x32_bf16 v[14:17], v[156:159], v[160:163], v[14:17]
	ds_read_b128 v[102:105], v142 offset:6144
	s_add_u32 m0, s22, 0x8c00
	v_add_u32_e32 v180, 0x8040, v176
	global_load_lds_dwordx4 v180, s[6:7]
	v_mfma_f32_16x16x32_bf16 v[18:21], v[144:147], v[164:167], v[18:21]
	ds_read_b128 v[106:109], v141
	s_add_u32 m0, s22, 0xc000
	v_mov_b32_e32 v179, v176
	global_load_lds_dwordx4 v179, s[8:9]
	v_mfma_f32_16x16x32_bf16 v[22:25], v[148:151], v[164:167], v[22:25]
	ds_read_b128 v[110:113], v141 offset:2048
	s_add_u32 m0, s22, 0xc400
	v_add_u32_e32 v180, 0x40, v176
	global_load_lds_dwordx4 v180, s[8:9]
	v_mfma_f32_16x16x32_bf16 v[26:29], v[152:155], v[164:167], v[26:29]
	ds_read_b128 v[114:117], v141 offset:4096
	s_add_u32 m0, s22, 0xc800
	v_add_u32_e32 v179, 0x8000, v176
	global_load_lds_dwordx4 v179, s[8:9]
	v_mfma_f32_16x16x32_bf16 v[30:33], v[156:159], v[164:167], v[30:33]
	ds_read_b128 v[118:121], v141 offset:6144
	s_add_u32 m0, s22, 0xcc00
	v_add_u32_e32 v180, 0x8040, v176
	global_load_lds_dwordx4 v180, s[8:9]
	v_mfma_f32_16x16x32_bf16 v[34:37], v[144:147], v[168:171], v[34:37]
	v_mfma_f32_16x16x32_bf16 v[38:41], v[148:151], v[168:171], v[38:41]
	v_mfma_f32_16x16x32_bf16 v[42:45], v[152:155], v[168:171], v[42:45]
	v_mfma_f32_16x16x32_bf16 v[46:49], v[156:159], v[168:171], v[46:49]
	v_mfma_f32_16x16x32_bf16 v[50:53], v[144:147], v[172:175], v[50:53]
	v_mfma_f32_16x16x32_bf16 v[54:57], v[148:151], v[172:175], v[54:57]
	v_mfma_f32_16x16x32_bf16 v[58:61], v[152:155], v[172:175], v[58:61]
	v_mfma_f32_16x16x32_bf16 v[62:65], v[156:159], v[172:175], v[62:65]
	v_add_u32_e32 v176, 0x80, v176
	s_branch .Lg128_ip_epi

.Lg128_ip_epi:
	s_mov_b32 s3, 4
	s_cmp_lg_u32 s27, 1
	s_cbranch_scc1 .Lg128_ip_mfull_0
	s_and_b32 s3, s15, 1
	s_xor_b32 s3, s3, 1
	s_lshl_b32 s3, s3, 1
.Lg128_ip_mfull_0:
	v_cvt_pk_bf16_f32 v2, v2, v3
	v_cvt_pk_bf16_f32 v3, v4, v5
	v_cvt_pk_bf16_f32 v6, v6, v7
	v_cvt_pk_bf16_f32 v7, v8, v9
	v_cvt_pk_bf16_f32 v10, v10, v11
	v_cvt_pk_bf16_f32 v11, v12, v13
	v_cvt_pk_bf16_f32 v14, v14, v15
	v_cvt_pk_bf16_f32 v15, v16, v17
	s_cmp_gt_u32 s3, 0
	s_cbranch_scc0 .Lg128_ip_ms_0_0_0
	global_store_dwordx2 v178, v[2:3], s[10:11]
	global_store_dwordx2 v178, v[6:7], s[10:11] offset:32
.Lg128_ip_ms_0_0_0:
	s_cmp_gt_u32 s3, 2
	s_cbranch_scc0 .Lg128_ip_ms_0_0_1
	global_store_dwordx2 v178, v[10:11], s[10:11] offset:64
	global_store_dwordx2 v178, v[14:15], s[10:11] offset:96
.Lg128_ip_ms_0_0_1:
	v_add_u32_e32 v131, 0x14400, v178
	v_cvt_pk_bf16_f32 v18, v18, v19
	v_cvt_pk_bf16_f32 v19, v20, v21
	v_cvt_pk_bf16_f32 v22, v22, v23
	v_cvt_pk_bf16_f32 v23, v24, v25
	v_cvt_pk_bf16_f32 v26, v26, v27
	v_cvt_pk_bf16_f32 v27, v28, v29
	v_cvt_pk_bf16_f32 v30, v30, v31
	v_cvt_pk_bf16_f32 v31, v32, v33
	s_cmp_gt_u32 s3, 0
	s_cbranch_scc0 .Lg128_ip_ms_0_1_0
	global_store_dwordx2 v131, v[18:19], s[10:11]
	global_store_dwordx2 v131, v[22:23], s[10:11] offset:32
.Lg128_ip_ms_0_1_0:
	s_cmp_gt_u32 s3, 2
	s_cbranch_scc0 .Lg128_ip_ms_0_1_1
	global_store_dwordx2 v131, v[26:27], s[10:11] offset:64
	global_store_dwordx2 v131, v[30:31], s[10:11] offset:96
.Lg128_ip_ms_0_1_1:
	v_add_u32_e32 v131, 0x28800, v178
	v_cvt_pk_bf16_f32 v34, v34, v35
	v_cvt_pk_bf16_f32 v35, v36, v37
	v_cvt_pk_bf16_f32 v38, v38, v39
	v_cvt_pk_bf16_f32 v39, v40, v41
	v_cvt_pk_bf16_f32 v42, v42, v43
	v_cvt_pk_bf16_f32 v43, v44, v45
	v_cvt_pk_bf16_f32 v46, v46, v47
	v_cvt_pk_bf16_f32 v47, v48, v49
	s_cmp_gt_u32 s3, 0
	s_cbranch_scc0 .Lg128_ip_ms_0_2_0
	global_store_dwordx2 v131, v[34:35], s[10:11]
	global_store_dwordx2 v131, v[38:39], s[10:11] offset:32
.Lg128_ip_ms_0_2_0:
	s_cmp_gt_u32 s3, 2
	s_cbranch_scc0 .Lg128_ip_ms_0_2_1
	global_store_dwordx2 v131, v[42:43], s[10:11] offset:64
	global_store_dwordx2 v131, v[46:47], s[10:11] offset:96
.Lg128_ip_ms_0_2_1:
	v_add_u32_e32 v131, 0x3cc00, v178
	v_cvt_pk_bf16_f32 v50, v50, v51
	v_cvt_pk_bf16_f32 v51, v52, v53
	v_cvt_pk_bf16_f32 v54, v54, v55
	v_cvt_pk_bf16_f32 v55, v56, v57
	v_cvt_pk_bf16_f32 v58, v58, v59
	v_cvt_pk_bf16_f32 v59, v60, v61
	v_cvt_pk_bf16_f32 v62, v62, v63
	v_cvt_pk_bf16_f32 v63, v64, v65
	s_cmp_gt_u32 s3, 0
	s_cbranch_scc0 .Lg128_ip_ms_0_3_0
	global_store_dwordx2 v131, v[50:51], s[10:11]
	global_store_dwordx2 v131, v[54:55], s[10:11] offset:32
.Lg128_ip_ms_0_3_0:
	s_cmp_gt_u32 s3, 2
	s_cbranch_scc0 .Lg128_ip_ms_0_3_1
	global_store_dwordx2 v131, v[58:59], s[10:11] offset:64
	global_store_dwordx2 v131, v[62:63], s[10:11] offset:96
.Lg128_ip_ms_0_3_1:
	s_cmp_lg_u32 s16, 0
	s_cbranch_scc1 .Lg128_ip_tile
